# lru_m1 conv weights/bias: 20 lane-uniform loads per item replaced by 2 coalesced loads staged in the spare bytes of the wave LDS slice + ds_read_b128
# speedup vs baseline: 1.0008x; 1.0008x over previous
; __device__ __forceinline__ void ld8bf(const bf16_t* p, float (&o)[8]) { unpack8(*(const u32x4*)p, o); }
; __device__ __forceinline__ const float* in_ptr(const Args& a, int i) { asm volatile("" : "+s"(i)); return a.in[i]; }
; __device__ __forceinline__ void w_lru_m1(const Args& a, int l, unsigned char* ws, const bf16_t* proj, bf16_t* y, LAS unsigned char* wl, int b, int ck_, int h, int lane) {
;     ...
;     const int row0 = b * SEQ + 64 * ck_, lo = lane & 15, fq = lane >> 4;
;     const float* cw = in_ptr(a, I_LCW) + (size_t)l * 4 * 512; const float* cbias = in_ptr(a, I_LCB) + l * 512;
;     const bf16_t* gwt = (const bf16_t*)(ws + WS_GATE) + (size_t)l * 65536;
;     const bf16_t* waT = gwt + h * 4096; const bf16_t* wxT = gwt + 32768 + h * 4096;
;     const float* ba = in_ptr(a, I_BA) + l * 512 + 64 * h; const float* bx = in_ptr(a, I_BX) + l * 512 + 64 * h; const float* lam = in_ptr(a, I_LAM) + l * 512 + 64 * h;
;     bf16x8 nWa[2], nWx[2]; f32x4 nba, nbx, nlam;
; #pragma unroll
;     for (int kk = 0; kk < 2; ++kk) { nWa[kk] = *(const bf16x8*)(waT + lo * 64 + 32 * kk + 8 * fq); nWx[kk] = *(const bf16x8*)(wxT + lo * 64 + 32 * kk + 8 * fq); }
;     nba = *(const f32x4*)(ba + 4 * fq); nbx = *(const f32x4*)(bx + 4 * fq); nlam = *(const f32x4*)(lam + 4 * fq);
;     bf16x8 Xf[4][2];
; #pragma unroll
;     for (int kk = 0; kk < 2; ++kk) { const int ch0 = 64 * h + 32 * kk + 8 * fq; float w[4][8], bs[8];
; #pragma unroll
;         for (int j = 0; j < 8; ++j) { bs[j] = cbias[ch0 + j];
; #pragma unroll
;             for (int k = 0; k < 4; ++k) w[k][j] = cw[k * 512 + ch0 + j]; }
; #pragma unroll
;         for (int tb = 0; tb < 4; ++tb) { const int tok = 16 * tb + lo, t = 64 * ck_ + tok; float s[8];
; #pragma unroll
;             for (int j = 0; j < 8; ++j) s[j] = bs[j];
; #pragma unroll
;             for (int k = 0; k < 4; ++k) { const int tt = t - 3 + k; float x[8];
;                 ld8bf(proj + (size_t)(b * SEQ + (tt >= 0 ? tt : 0)) * NIN + C_LX + ch0, x);
.LBB0_520:
	s_lshr_b32 s20, s24, 8
	s_lshr_b32 s21, s24, 9
	s_add_i32 s20, s20, s24
	s_and_b32 s21, s21, 12
	s_add_i32 s20, s20, s21
	s_and_b32 s91, s20, 15
	s_cmp_gt_u32 s91, 7
	s_cbranch_scc1 .LBB0_519
	s_ashr_i32 s20, s24, 31
	s_ashr_i32 s90, s24, 4
	s_lshr_b32 s20, s20, 25
	s_add_i32 s27, s90, s20
	s_and_b32 s20, s27, 0xffffff80
	v_mov_b32_e32 v122, v144
	s_mov_b32 s34, 3
	s_sub_i32 s46, s90, s20
	s_ashr_i32 s35, s34, 31
	s_lshl_b32 s20, s46, 6
	s_lshl_b64 s[34:35], s[34:35], 3
	s_add_u32 s34, s0, s34
	s_addc_u32 s35, s1, s35
	s_load_dwordx2 s[40:41], s[34:35], 0x0
	s_mov_b32 s34, 4
	s_ashr_i32 s35, s34, 31
	s_lshl_b64 s[34:35], s[34:35], 3
	s_add_u32 s34, s0, s34
	s_addc_u32 s35, s1, s35
	s_lshl_b32 s21, s91, 13
	s_add_u32 s92, s2, s21
	s_addc_u32 s93, s3, 0
	s_load_dwordx2 s[42:43], s[34:35], 0x0
	s_add_u32 s34, s68, s21
	s_mov_b32 s44, 6
	s_addc_u32 s35, s70, 0
	s_ashr_i32 s45, s44, 31
	s_lshl_b64 s[44:45], s[44:45], 3
	s_add_u32 s44, s0, s44
	s_addc_u32 s45, s1, s45
	s_waitcnt lgkmcnt(0)
	s_mov_b32 s48, 8
	s_load_dwordx2 s[44:45], s[44:45], 0x0
	s_ashr_i32 s49, s48, 31
	s_lshl_b32 s21, s91, 6
	s_lshl_b64 s[48:49], s[48:49], 3
	s_add_u32 s48, s0, s48
	s_addc_u32 s49, s1, s49
	s_load_dwordx2 s[48:49], s[48:49], 0x0
	v_ashrrev_i32_e32 v8, 4, v122
	v_and_b32_e32 v136, 15, v122
	v_lshlrev_b32_e32 v4, 3, v8
	v_lshlrev_b32_e32 v2, 7, v136
	s_waitcnt lgkmcnt(0)
	s_add_u32 s47, s48, s88
	s_mov_b32 s48, 9
	s_addc_u32 s50, s49, s89
	s_ashr_i32 s49, s48, 31
	s_lshl_b64 s[48:49], s[48:49], 3
	s_add_u32 s48, s0, s48
	s_addc_u32 s49, s1, s49
	s_add_u32 s48, s78, 0x3b00000
	s_addc_u32 s49, s79, 0x0
	v_ashrrev_i32_e32 v5, 31, v4
	v_lshl_add_u64 v[0:1], s[92:93], 0, v[2:3]
	v_lshlrev_b64 v[100:101], 1, v[4:5]
	v_lshl_add_u64 v[0:1], v[0:1], 0, v[100:101]
	s_waitcnt lgkmcnt(0)
	s_add_u32 s51, s48, s88
	s_addc_u32 s52, s49, s89
	s_lshl_b32 s27, s27, 6
	s_and_b32 s27, s27, 0xffffe000
	s_add_u32 s48, s40, s96
	s_addc_u32 s49, s41, s97
	s_add_u32 s42, s42, s88
	s_addc_u32 s43, s43, s89
	s_add_u32 s40, s44, s88
	s_addc_u32 s41, s45, s89
	s_lshl_b32 s53, s91, 8
	s_add_u32 s40, s40, s53
	v_lshl_add_u64 v[6:7], s[34:35], 0, v[2:3]
	s_addc_u32 s41, s41, 0
	v_lshl_add_u64 v[6:7], v[6:7], 0, v[100:101]
	global_load_dwordx4 v[52:55], v[0:1], off
	global_load_dwordx4 v[56:59], v[6:7], off
	global_load_dwordx4 v[60:63], v[0:1], off offset:64
	global_load_dwordx4 v[64:67], v[6:7], off offset:64
	s_add_u32 s44, s47, s53
	v_lshlrev_b32_e32 v0, 2, v8
	s_addc_u32 s45, s50, 0
	v_ashrrev_i32_e32 v1, 31, v0
	s_add_u32 s50, s51, s53
	v_lshlrev_b64 v[6:7], 2, v[0:1]
	s_addc_u32 s51, s52, 0
	v_lshl_add_u64 v[108:109], s[40:41], 0, v[6:7]
	s_add_i32 s40, s20, -3
	v_add_u32_e32 v78, s21, v4
	v_lshl_add_u64 v[110:111], s[44:45], 0, v[6:7]
	v_lshl_add_u64 v[112:113], s[50:51], 0, v[6:7]
	v_ashrrev_i32_e32 v79, 31, v78
	v_add_u32_e32 v6, s40, v136
	v_lshlrev_b64 v[4:5], 2, v[78:79]
	v_cmp_lt_i32_e64 s[50:51], -1, v6
	v_lshl_add_u64 v[76:77], s[42:43], 0, v[4:5]
	v_lshl_add_u64 v[86:87], s[48:49], 0, v[4:5]
	v_mul_u32_u24_e32 v186, 0x7e0, v8
	v_lshl_add_u32 v186, v136, 4, v186
	v_mov_b32_e32 v187, 0
	v_lshl_add_u64 v[188:189], v[86:87], 0, v[186:187]
	global_load_dwordx4 v[146:149], v[188:189], off
	v_lshlrev_b32_e32 v186, 4, v136
	v_lshlrev_b32_e32 v187, 5, v8
	v_sub_u32_e32 v186, v186, v187
	v_ashrrev_i32_e32 v187, 31, v186
	v_lshl_add_u64 v[188:189], v[76:77], 0, v[186:187]
	global_load_dwordx4 v[150:153], v[188:189], off
	s_mov_b64 s[42:43], 0x1000
	v_cndmask_b32_e64 v4, 0, v6, s[50:51]
	v_lshl_add_u64 v[36:37], v[86:87], 0, s[42:43]
	s_mov_b64 s[42:43], 0x1800
	v_lshl_add_u64 v[80:81], v[78:79], 1, s[8:9]
	v_add_u32_e32 v79, s27, v4
	v_lshl_add_u64 v[82:83], v[86:87], 0, s[42:43]
	v_max_i32_e32 v4, -1, v6
	s_or_b32 s80, s27, 1
	v_add_u32_e32 v92, s80, v4
	v_max_i32_e32 v4, -2, v6
	s_or_b32 s81, s27, 2
	v_add_u32_e32 v93, s81, v4
	s_cmp_gt_i32 s46, -1
	v_or_b32_e32 v4, s20, v136
	s_cselect_b64 s[42:43], -1, 0
	v_cndmask_b32_e64 v4, 0, v4, s[42:43]
	v_add_u32_e32 v94, s27, v4
	global_load_dwordx4 v[48:51], v[108:109], off
	global_load_dwordx4 v[44:47], v[110:111], off
	global_load_dwordx4 v[88:91], v[112:113], off
	v_lshl_add_u32 v95, v8, 5, s6
	v_cmp_lt_i32_e64 s[48:49], -2, v6
	v_cmp_lt_i32_e64 s[44:45], -3, v6
	s_nop 0
	v_add_co_u32_e32 v96, vcc, s73, v86
	v_mad_u32_u24 v121, v136, s76, v95
	s_nop 0
	v_addc_co_u32_e32 v97, vcc, 0, v87, vcc
	s_nop 0
	s_nop 0
	v_add_u32_e32 v186, s20, v136
	v_add_u32_e32 v187, -16, v186
	v_max_i32_e32 v187, 0, v187
	v_add_u32_e32 v187, s27, v187
	v_add_u32_e32 v186, s27, v186
	v_mad_i64_i32 v[188:189], s[46:47], v187, s72, v[80:81]
	global_load_dwordx4 v[222:225], v[188:189], off
	global_load_dwordx4 v[242:245], v[188:189], off offset:64
	v_mad_i64_i32 v[188:189], s[46:47], v186, s72, v[80:81]
	global_load_dwordx4 v[226:229], v[188:189], off
	global_load_dwordx4 v[246:249], v[188:189], off offset:64
	v_add_u32_e32 v187, 16, v186
	v_mad_i64_i32 v[188:189], s[46:47], v187, s72, v[80:81]
	global_load_dwordx4 v[230:233], v[188:189], off
	global_load_dwordx4 v[250:253], v[188:189], off offset:64
	v_add_u32_e32 v187, 32, v186
	v_mad_i64_i32 v[188:189], s[46:47], v187, s72, v[80:81]
	global_load_dwordx4 v[234:237], v[188:189], off
	global_load_dwordx4 v[190:193], v[188:189], off offset:64
	v_add_u32_e32 v187, 48, v186
	v_mad_i64_i32 v[188:189], s[46:47], v187, s72, v[80:81]
	global_load_dwordx4 v[238:241], v[188:189], off
	global_load_dwordx4 v[194:197], v[188:189], off offset:64
	v_or_b32_e32 v140, 16, v136
	v_or_b32_e32 v139, 32, v136
	v_or_b32_e32 v137, 48, v136
	v_mov_b64_e32 v[102:103], s[8:9]
	s_waitcnt vmcnt(13)
; __device__ __forceinline__ void ld8bf(const bf16_t* p, float (&o)[8]) { unpack8(*(const u32x4*)p, o); }
; __device__ __forceinline__ bf16x8 pack_frag(const float (&v)[8]) { return __builtin_bit_cast(bf16x8, pack8(v)); }
; __device__ __forceinline__ void w_lru_m1(const Args& a, int l, unsigned char* ws, const bf16_t* proj, bf16_t* y, LAS unsigned char* wl, int b, int ck_, int h, int lane) {
;     ...
;     for (int kk = 0; kk < 2; ++kk) { const int ch0 = 64 * h + 32 * kk + 8 * fq; float w[4][8], bs[8];
; #pragma unroll
;         for (int j = 0; j < 8; ++j) { bs[j] = cbias[ch0 + j];
; #pragma unroll
;             for (int k = 0; k < 4; ++k) w[k][j] = cw[k * 512 + ch0 + j]; }
; #pragma unroll
;         for (int tb = 0; tb < 4; ++tb) { const int tok = 16 * tb + lo, t = 64 * ck_ + tok; float s[8];
; #pragma unroll
;             for (int j = 0; j < 8; ++j) s[j] = bs[j];
; #pragma unroll
;             for (int k = 0; k < 4; ++k) { const int tt = t - 3 + k; float x[8];
;                 ld8bf(proj + (size_t)(b * SEQ + (tt >= 0 ? tt : 0)) * NIN + C_LX + ch0, x);
; #pragma unroll
;                 for (int j = 0; j < 8; ++j) s[j] += (tt >= 0 ? w[k][j] : 0.f) * x[j]; }
;             Xf[tb][kk] = pack_frag(s);
; #pragma unroll
;             for (int j = 0; j < 8; ++j) xcf[tok * 65 + 32 * kk + 8 * fq + j] = s[j]; }
	v_lshl_add_u32 v198, v144, 4, s6
	v_lshl_add_u32 v154, v136, 4, s6
	v_mov_b32_e32 v199, v95
	ds_write_b128 v198, v[146:149] offset:16640
	ds_write_b128 v154, v[150:153] offset:17664
	ds_read_b128 v[32:35], v199 offset:16640
	ds_read_b128 v[24:27], v199 offset:16656
	ds_read_b128 v[40:43], v199 offset:16896
	ds_read_b128 v[28:31], v199 offset:16912
	ds_read_b128 v[68:71], v199 offset:17152
	ds_read_b128 v[36:39], v199 offset:17168
	ds_read_b128 v[104:107], v199 offset:17408
	ds_read_b128 v[114:117], v199 offset:17424
	ds_read_b128 v[4:7], v199 offset:17664
	ds_read_b128 v[20:23], v199 offset:17680
	s_waitcnt vmcnt(0) lgkmcnt(0)
	v_mov_b32_dpp v72, v222 row_ror:3 row_mask:0xf bank_mask:0xf
	v_mov_b32_dpp v73, v223 row_ror:3 row_mask:0xf bank_mask:0xf
	v_mov_b32_dpp v74, v224 row_ror:3 row_mask:0xf bank_mask:0xf
	v_mov_b32_dpp v75, v225 row_ror:3 row_mask:0xf bank_mask:0xf
	v_mov_b32_dpp v72, v226 row_shr:3 row_mask:0xf bank_mask:0xf
	v_mov_b32_dpp v73, v227 row_shr:3 row_mask:0xf bank_mask:0xf
	v_mov_b32_dpp v74, v228 row_shr:3 row_mask:0xf bank_mask:0xf
	v_mov_b32_dpp v75, v229 row_shr:3 row_mask:0xf bank_mask:0xf
	v_mov_b32_dpp v16, v222 row_ror:2 row_mask:0xf bank_mask:0xf
	v_mov_b32_dpp v17, v223 row_ror:2 row_mask:0xf bank_mask:0xf
	v_mov_b32_dpp v18, v224 row_ror:2 row_mask:0xf bank_mask:0xf
	v_mov_b32_dpp v19, v225 row_ror:2 row_mask:0xf bank_mask:0xf
	v_mov_b32_dpp v16, v226 row_shr:2 row_mask:0xf bank_mask:0xf
	v_mov_b32_dpp v17, v227 row_shr:2 row_mask:0xf bank_mask:0xf
	v_mov_b32_dpp v18, v228 row_shr:2 row_mask:0xf bank_mask:0xf
	v_mov_b32_dpp v19, v229 row_shr:2 row_mask:0xf bank_mask:0xf
	v_mov_b32_dpp v12, v222 row_ror:1 row_mask:0xf bank_mask:0xf
	v_mov_b32_dpp v13, v223 row_ror:1 row_mask:0xf bank_mask:0xf
	v_mov_b32_dpp v14, v224 row_ror:1 row_mask:0xf bank_mask:0xf
	v_mov_b32_dpp v15, v225 row_ror:1 row_mask:0xf bank_mask:0xf
	v_mov_b32_dpp v12, v226 row_shr:1 row_mask:0xf bank_mask:0xf
	v_mov_b32_dpp v13, v227 row_shr:1 row_mask:0xf bank_mask:0xf
	v_mov_b32_dpp v14, v228 row_shr:1 row_mask:0xf bank_mask:0xf
	v_mov_b32_dpp v15, v229 row_shr:1 row_mask:0xf bank_mask:0xf
	v_mov_b64_e32 v[8:9], v[226:227]
	v_mov_b64_e32 v[10:11], v[228:229]
	v_lshlrev_b32_e32 v82, 16, v72
	v_lshlrev_b32_e32 v84, 16, v73
	v_and_b32_e32 v83, 0xffff0000, v72
	v_and_b32_e32 v85, 0xffff0000, v73
	v_cndmask_b32_e64 v73, 0, v33, s[50:51]
	v_cndmask_b32_e64 v72, 0, v32, s[50:51]
	v_cndmask_b32_e64 v99, 0, v35, s[50:51]
	v_cndmask_b32_e64 v98, 0, v34, s[50:51]
	v_pk_fma_f32 v[84:85], v[98:99], v[84:85], v[6:7]
	v_pk_fma_f32 v[72:73], v[72:73], v[82:83], v[4:5]
	v_lshlrev_b32_e32 v82, 16, v17
	v_lshlrev_b32_e32 v98, 16, v16
	v_and_b32_e32 v83, 0xffff0000, v17
	v_and_b32_e32 v99, 0xffff0000, v16
	v_cndmask_b32_e64 v17, 0, v43, s[48:49]
	v_cndmask_b32_e64 v16, 0, v42, s[48:49]
	v_cndmask_b32_e64 v119, 0, v41, s[48:49]
	v_cndmask_b32_e64 v118, 0, v40, s[48:49]
	v_pk_fma_f32 v[72:73], v[118:119], v[98:99], v[72:73]
	v_pk_fma_f32 v[16:17], v[16:17], v[82:83], v[84:85]
	v_lshlrev_b32_e32 v82, 16, v12
	v_lshlrev_b32_e32 v84, 16, v13
	v_and_b32_e32 v83, 0xffff0000, v12
	v_and_b32_e32 v85, 0xffff0000, v13
	v_cndmask_b32_e64 v13, 0, v69, s[44:45]
	v_cndmask_b32_e64 v12, 0, v68, s[44:45]
	v_cndmask_b32_e64 v99, 0, v71, s[44:45]
	v_cndmask_b32_e64 v98, 0, v70, s[44:45]
	v_pk_fma_f32 v[16:17], v[98:99], v[84:85], v[16:17]
	v_pk_fma_f32 v[12:13], v[12:13], v[82:83], v[72:73]
	v_lshlrev_b32_e32 v84, 16, v9
	v_lshlrev_b32_e32 v98, 16, v8
	v_and_b32_e32 v85, 0xffff0000, v9
	v_and_b32_e32 v99, 0xffff0000, v8
	v_cndmask_b32_e64 v73, 0, v107, s[42:43]
	v_cndmask_b32_e64 v72, 0, v106, s[42:43]
	v_cndmask_b32_e64 v83, 0, v105, s[42:43]
	v_cndmask_b32_e64 v82, 0, v104, s[42:43]
	v_pk_fma_f32 v[8:9], v[82:83], v[98:99], v[12:13]
	v_pk_fma_f32 v[12:13], v[72:73], v[84:85], v[16:17]
	v_cvt_pk_bf16_f32 v16, v8, v9
	v_cvt_pk_bf16_f32 v17, v12, v13
	ds_write2_b32 v121, v12, v13 offset0:2 offset1:3
	ds_write2_b32 v121, v8, v9 offset1:1
	v_lshlrev_b32_e32 v8, 16, v74
	v_lshlrev_b32_e32 v12, 16, v75
	v_and_b32_e32 v9, 0xffff0000, v74
	v_and_b32_e32 v13, 0xffff0000, v75
	v_cndmask_b32_e64 v75, 0, v25, s[50:51]
	v_cndmask_b32_e64 v74, 0, v24, s[50:51]
	v_cndmask_b32_e64 v85, 0, v27, s[50:51]
	v_cndmask_b32_e64 v84, 0, v26, s[50:51]
	v_pk_fma_f32 v[12:13], v[84:85], v[12:13], v[22:23]
	v_pk_fma_f32 v[8:9], v[74:75], v[8:9], v[20:21]
	v_lshlrev_b32_e32 v74, 16, v19
	v_lshlrev_b32_e32 v84, 16, v18
	v_and_b32_e32 v75, 0xffff0000, v19
	v_and_b32_e32 v85, 0xffff0000, v18
	v_cndmask_b32_e64 v19, 0, v31, s[48:49]
	v_cndmask_b32_e64 v18, 0, v30, s[48:49]
	v_cndmask_b32_e64 v99, 0, v29, s[48:49]
	v_cndmask_b32_e64 v98, 0, v28, s[48:49]
	v_pk_fma_f32 v[8:9], v[98:99], v[84:85], v[8:9]
	v_pk_fma_f32 v[12:13], v[18:19], v[74:75], v[12:13]
	v_lshlrev_b32_e32 v18, 16, v14
	v_lshlrev_b32_e32 v74, 16, v15
	v_and_b32_e32 v19, 0xffff0000, v14
	v_and_b32_e32 v75, 0xffff0000, v15
	v_cndmask_b32_e64 v15, 0, v37, s[44:45]
	v_cndmask_b32_e64 v14, 0, v36, s[44:45]
	v_cndmask_b32_e64 v85, 0, v39, s[44:45]
	v_cndmask_b32_e64 v84, 0, v38, s[44:45]
	v_pk_fma_f32 v[12:13], v[84:85], v[74:75], v[12:13]
	v_pk_fma_f32 v[8:9], v[14:15], v[18:19], v[8:9]
	v_lshlrev_b32_e32 v14, 16, v11
	v_lshlrev_b32_e32 v18, 16, v10
	v_and_b32_e32 v15, 0xffff0000, v11
	v_and_b32_e32 v19, 0xffff0000, v10
	v_cndmask_b32_e64 v75, 0, v117, s[42:43]
	v_cndmask_b32_e64 v74, 0, v116, s[42:43]
	v_cndmask_b32_e64 v85, 0, v115, s[42:43]
	v_cndmask_b32_e64 v84, 0, v114, s[42:43]
	v_add_u32_e32 v98, s40, v140
	v_pk_fma_f32 v[8:9], v[84:85], v[18:19], v[8:9]
	v_pk_fma_f32 v[10:11], v[74:75], v[14:15], v[12:13]
	v_cmp_lt_i32_e64 s[62:63], -1, v98
; __device__ __forceinline__ void ld8bf(const bf16_t* p, float (&o)[8]) { unpack8(*(const u32x4*)p, o); }
; __device__ __forceinline__ bf16x8 pack_frag(const float (&v)[8]) { return __builtin_bit_cast(bf16x8, pack8(v)); }
; __device__ __forceinline__ void w_lru_m1(const Args& a, int l, unsigned char* ws, const bf16_t* proj, bf16_t* y, LAS unsigned char* wl, int b, int ck_, int h, int lane) {
;     ...
;         for (int tb = 0; tb < 4; ++tb) { const int tok = 16 * tb + lo, t = 64 * ck_ + tok; float s[8];
; #pragma unroll
;             for (int j = 0; j < 8; ++j) s[j] = bs[j];
; #pragma unroll
;             for (int k = 0; k < 4; ++k) { const int tt = t - 3 + k; float x[8];
;                 ld8bf(proj + (size_t)(b * SEQ + (tt >= 0 ? tt : 0)) * NIN + C_LX + ch0, x);
; #pragma unroll
;                 for (int j = 0; j < 8; ++j) s[j] += (tt >= 0 ? w[k][j] : 0.f) * x[j]; }
;             Xf[tb][kk] = pack_frag(s);
; #pragma unroll
;             for (int j = 0; j < 8; ++j) xcf[tok * 65 + 32 * kk + 8 * fq + j] = s[j]; }
	v_cvt_pk_bf16_f32 v18, v8, v9
	ds_write2_b32 v121, v10, v11 offset0:6 offset1:7
	ds_write2_b32 v121, v8, v9 offset0:4 offset1:5
	v_cndmask_b32_e64 v8, 0, v98, s[62:63]
	v_cmp_lt_i32_e64 s[60:61], -2, v98
	v_max_i32_e32 v12, -1, v98
	v_cmp_lt_i32_e64 s[58:59], -3, v98
	v_max_i32_e32 v98, -2, v98
	v_add_u32_e32 v142, s81, v98
	v_add_u32_e32 v134, s27, v8
	v_add_u32_e32 v135, s80, v12
	v_mov_b32_dpp v104, v226 row_ror:1 row_mask:0xf bank_mask:0xf
	v_mov_b32_dpp v105, v227 row_ror:1 row_mask:0xf bank_mask:0xf
	v_mov_b32_dpp v106, v228 row_ror:1 row_mask:0xf bank_mask:0xf
	v_mov_b32_dpp v107, v229 row_ror:1 row_mask:0xf bank_mask:0xf
	v_mov_b32_dpp v104, v230 row_shr:1 row_mask:0xf bank_mask:0xf
	v_mov_b32_dpp v105, v231 row_shr:1 row_mask:0xf bank_mask:0xf
	v_mov_b32_dpp v106, v232 row_shr:1 row_mask:0xf bank_mask:0xf
	v_mov_b32_dpp v107, v233 row_shr:1 row_mask:0xf bank_mask:0xf
	v_or_b32_e32 v98, s20, v140
	v_cvt_pk_bf16_f32 v19, v10, v11
	v_mov_b32_dpp v8, v226 row_ror:3 row_mask:0xf bank_mask:0xf
	v_mov_b32_dpp v9, v227 row_ror:3 row_mask:0xf bank_mask:0xf
	v_mov_b32_dpp v10, v228 row_ror:3 row_mask:0xf bank_mask:0xf
	v_mov_b32_dpp v11, v229 row_ror:3 row_mask:0xf bank_mask:0xf
	v_mov_b32_dpp v8, v230 row_shr:3 row_mask:0xf bank_mask:0xf
	v_mov_b32_dpp v9, v231 row_shr:3 row_mask:0xf bank_mask:0xf
	v_mov_b32_dpp v10, v232 row_shr:3 row_mask:0xf bank_mask:0xf
	v_mov_b32_dpp v11, v233 row_shr:3 row_mask:0xf bank_mask:0xf
	v_cndmask_b32_e64 v98, 0, v98, s[42:43]
	v_mov_b32_dpp v12, v226 row_ror:2 row_mask:0xf bank_mask:0xf
	v_mov_b32_dpp v13, v227 row_ror:2 row_mask:0xf bank_mask:0xf
	v_mov_b32_dpp v14, v228 row_ror:2 row_mask:0xf bank_mask:0xf
	v_mov_b32_dpp v15, v229 row_ror:2 row_mask:0xf bank_mask:0xf
	v_mov_b32_dpp v12, v230 row_shr:2 row_mask:0xf bank_mask:0xf
	v_mov_b32_dpp v13, v231 row_shr:2 row_mask:0xf bank_mask:0xf
	v_mov_b32_dpp v14, v232 row_shr:2 row_mask:0xf bank_mask:0xf
	v_mov_b32_dpp v15, v233 row_shr:2 row_mask:0xf bank_mask:0xf
	v_add_u32_e32 v143, s27, v98
	v_mov_b64_e32 v[114:115], v[230:231]
	v_mov_b64_e32 v[116:117], v[232:233]
	v_mov_b32_e32 v98, 0x1040
	v_mad_u32_u24 v123, v136, s76, v98
	v_cndmask_b32_e64 v127, 0, v35, s[62:63]
	v_cndmask_b32_e64 v126, 0, v34, s[62:63]
	v_cndmask_b32_e64 v129, 0, v41, s[60:61]
	v_cndmask_b32_e64 v128, 0, v40, s[60:61]
	v_add_u32_e32 v125, v95, v123
	s_waitcnt vmcnt(0) lgkmcnt(0)
	v_lshlrev_b32_e32 v98, 16, v8
	v_lshlrev_b32_e32 v118, 16, v9
	v_and_b32_e32 v99, 0xffff0000, v8
	v_and_b32_e32 v119, 0xffff0000, v9
	v_cndmask_b32_e64 v9, 0, v33, s[62:63]
	v_cndmask_b32_e64 v8, 0, v32, s[62:63]
	v_pk_fma_f32 v[118:119], v[126:127], v[118:119], v[6:7]
	v_pk_fma_f32 v[8:9], v[8:9], v[98:99], v[4:5]
	v_lshlrev_b32_e32 v98, 16, v13
	v_lshlrev_b32_e32 v126, 16, v12
	v_and_b32_e32 v99, 0xffff0000, v13
	v_and_b32_e32 v127, 0xffff0000, v12
	v_cndmask_b32_e64 v13, 0, v43, s[60:61]
	v_cndmask_b32_e64 v12, 0, v42, s[60:61]
	v_pk_fma_f32 v[8:9], v[128:129], v[126:127], v[8:9]
	v_pk_fma_f32 v[12:13], v[12:13], v[98:99], v[118:119]
	v_lshlrev_b32_e32 v98, 16, v104
	v_lshlrev_b32_e32 v118, 16, v105
	v_and_b32_e32 v99, 0xffff0000, v104
	v_and_b32_e32 v119, 0xffff0000, v105
	v_cndmask_b32_e64 v105, 0, v69, s[58:59]
	v_cndmask_b32_e64 v104, 0, v68, s[58:59]
	v_cndmask_b32_e64 v127, 0, v71, s[58:59]
	v_cndmask_b32_e64 v126, 0, v70, s[58:59]
	v_pk_fma_f32 v[12:13], v[126:127], v[118:119], v[12:13]
	v_pk_fma_f32 v[8:9], v[104:105], v[98:99], v[8:9]
	v_lshlrev_b32_e32 v98, 16, v115
	v_lshlrev_b32_e32 v104, 16, v114
	v_and_b32_e32 v99, 0xffff0000, v115
	v_and_b32_e32 v105, 0xffff0000, v114
	v_pk_fma_f32 v[8:9], v[82:83], v[104:105], v[8:9]
	v_pk_fma_f32 v[98:99], v[72:73], v[98:99], v[12:13]
	v_cvt_pk_bf16_f32 v12, v8, v9
	v_cvt_pk_bf16_f32 v13, v98, v99
	ds_write2_b32 v125, v98, v99 offset0:2 offset1:3
	ds_write2_b32 v125, v8, v9 offset1:1
	v_lshlrev_b32_e32 v8, 16, v10
	v_lshlrev_b32_e32 v98, 16, v11
	v_and_b32_e32 v9, 0xffff0000, v10
	v_and_b32_e32 v99, 0xffff0000, v11
	v_cndmask_b32_e64 v11, 0, v25, s[62:63]
	v_cndmask_b32_e64 v10, 0, v24, s[62:63]
	v_cndmask_b32_e64 v105, 0, v27, s[62:63]
	v_cndmask_b32_e64 v104, 0, v26, s[62:63]
	v_pk_fma_f32 v[98:99], v[104:105], v[98:99], v[22:23]
	v_pk_fma_f32 v[8:9], v[10:11], v[8:9], v[20:21]
	v_lshlrev_b32_e32 v10, 16, v15
	v_lshlrev_b32_e32 v104, 16, v14
	v_and_b32_e32 v11, 0xffff0000, v15
	v_and_b32_e32 v105, 0xffff0000, v14
	v_cndmask_b32_e64 v15, 0, v31, s[60:61]
	v_cndmask_b32_e64 v14, 0, v30, s[60:61]
	v_cndmask_b32_e64 v115, 0, v29, s[60:61]
	v_cndmask_b32_e64 v114, 0, v28, s[60:61]
	v_pk_fma_f32 v[8:9], v[114:115], v[104:105], v[8:9]
	v_pk_fma_f32 v[10:11], v[14:15], v[10:11], v[98:99]
	v_lshlrev_b32_e32 v14, 16, v106
	v_lshlrev_b32_e32 v98, 16, v107
	v_and_b32_e32 v15, 0xffff0000, v106
	v_and_b32_e32 v99, 0xffff0000, v107
	v_cndmask_b32_e64 v105, 0, v37, s[58:59]
	v_cndmask_b32_e64 v104, 0, v36, s[58:59]
	v_cndmask_b32_e64 v107, 0, v39, s[58:59]
	v_cndmask_b32_e64 v106, 0, v38, s[58:59]
	v_pk_fma_f32 v[10:11], v[106:107], v[98:99], v[10:11]
	v_pk_fma_f32 v[8:9], v[104:105], v[14:15], v[8:9]
	v_lshlrev_b32_e32 v14, 16, v117
	v_lshlrev_b32_e32 v98, 16, v116
	v_and_b32_e32 v15, 0xffff0000, v117
	v_and_b32_e32 v99, 0xffff0000, v116
	v_add_u32_e32 v114, s40, v139
	v_pk_fma_f32 v[8:9], v[84:85], v[98:99], v[8:9]
	v_pk_fma_f32 v[10:11], v[74:75], v[14:15], v[10:11]
	v_cmp_lt_i32_e64 s[56:57], -1, v114
	v_cvt_pk_bf16_f32 v14, v8, v9
	ds_write2_b32 v125, v10, v11 offset0:6 offset1:7
	ds_write2_b32 v125, v8, v9 offset0:4 offset1:5
	v_cndmask_b32_e64 v8, 0, v114, s[56:57]
	v_max_i32_e32 v98, -1, v114
	v_add_u32_e32 v130, s27, v8
	v_add_u32_e32 v131, s80, v98
; __device__ __forceinline__ void ld8bf(const bf16_t* p, float (&o)[8]) { unpack8(*(const u32x4*)p, o); }
; __device__ __forceinline__ bf16x8 pack_frag(const float (&v)[8]) { return __builtin_bit_cast(bf16x8, pack8(v)); }
; __device__ __forceinline__ void w_lru_m1(const Args& a, int l, unsigned char* ws, const bf16_t* proj, bf16_t* y, LAS unsigned char* wl, int b, int ck_, int h, int lane) {
;     ...
;         for (int tb = 0; tb < 4; ++tb) { const int tok = 16 * tb + lo, t = 64 * ck_ + tok; float s[8];
; #pragma unroll
;             for (int j = 0; j < 8; ++j) s[j] = bs[j];
; #pragma unroll
;             for (int k = 0; k < 4; ++k) { const int tt = t - 3 + k; float x[8];
;                 ld8bf(proj + (size_t)(b * SEQ + (tt >= 0 ? tt : 0)) * NIN + C_LX + ch0, x);
; #pragma unroll
;                 for (int j = 0; j < 8; ++j) s[j] += (tt >= 0 ? w[k][j] : 0.f) * x[j]; }
;             Xf[tb][kk] = pack_frag(s);
; #pragma unroll
;             for (int j = 0; j < 8; ++j) xcf[tok * 65 + 32 * kk + 8 * fq + j] = s[j]; }
	v_cvt_pk_bf16_f32 v15, v10, v11
	v_mov_b32_dpp v8, v230 row_ror:3 row_mask:0xf bank_mask:0xf
	v_mov_b32_dpp v9, v231 row_ror:3 row_mask:0xf bank_mask:0xf
	v_mov_b32_dpp v10, v232 row_ror:3 row_mask:0xf bank_mask:0xf
	v_mov_b32_dpp v11, v233 row_ror:3 row_mask:0xf bank_mask:0xf
	v_mov_b32_dpp v8, v234 row_shr:3 row_mask:0xf bank_mask:0xf
	v_mov_b32_dpp v9, v235 row_shr:3 row_mask:0xf bank_mask:0xf
	v_mov_b32_dpp v10, v236 row_shr:3 row_mask:0xf bank_mask:0xf
	v_mov_b32_dpp v11, v237 row_shr:3 row_mask:0xf bank_mask:0xf
	v_cmp_lt_i32_e64 s[54:55], -2, v114
	v_mov_b32_dpp v104, v230 row_ror:2 row_mask:0xf bank_mask:0xf
	v_mov_b32_dpp v105, v231 row_ror:2 row_mask:0xf bank_mask:0xf
	v_mov_b32_dpp v106, v232 row_ror:2 row_mask:0xf bank_mask:0xf
	v_mov_b32_dpp v107, v233 row_ror:2 row_mask:0xf bank_mask:0xf
	v_mov_b32_dpp v104, v234 row_shr:2 row_mask:0xf bank_mask:0xf
	v_mov_b32_dpp v105, v235 row_shr:2 row_mask:0xf bank_mask:0xf
	v_mov_b32_dpp v106, v236 row_shr:2 row_mask:0xf bank_mask:0xf
	v_mov_b32_dpp v107, v237 row_shr:2 row_mask:0xf bank_mask:0xf
	v_max_i32_e32 v98, -2, v114
	v_add_u32_e32 v132, s81, v98
	v_cmp_lt_i32_e64 s[52:53], -3, v114
	v_mov_b32_dpp v114, v230 row_ror:1 row_mask:0xf bank_mask:0xf
	v_mov_b32_dpp v115, v231 row_ror:1 row_mask:0xf bank_mask:0xf
	v_mov_b32_dpp v116, v232 row_ror:1 row_mask:0xf bank_mask:0xf
	v_mov_b32_dpp v117, v233 row_ror:1 row_mask:0xf bank_mask:0xf
	v_mov_b32_dpp v114, v234 row_shr:1 row_mask:0xf bank_mask:0xf
	v_mov_b32_dpp v115, v235 row_shr:1 row_mask:0xf bank_mask:0xf
	v_mov_b32_dpp v116, v236 row_shr:1 row_mask:0xf bank_mask:0xf
	v_mov_b32_dpp v117, v237 row_shr:1 row_mask:0xf bank_mask:0xf
	v_or_b32_e32 v98, s20, v139
	v_cndmask_b32_e64 v98, 0, v98, s[42:43]
	v_add_u32_e32 v133, s27, v98
	v_mov_b64_e32 v[126:127], v[234:235]
	v_mov_b64_e32 v[128:129], v[236:237]
	v_mov_b32_e32 v98, 0x2080
	v_mad_u32_u24 v141, v136, s76, v98
	v_cndmask_b32_e64 v147, 0, v35, s[56:57]
	v_cndmask_b32_e64 v146, 0, v34, s[56:57]
	v_cndmask_b32_e64 v149, 0, v41, s[54:55]
	v_cndmask_b32_e64 v148, 0, v40, s[54:55]
	v_add_u32_e32 v124, v95, v141
	s_waitcnt vmcnt(0) lgkmcnt(0)
	v_lshlrev_b32_e32 v98, 16, v8
	v_lshlrev_b32_e32 v118, 16, v9
	v_and_b32_e32 v99, 0xffff0000, v8
	v_and_b32_e32 v119, 0xffff0000, v9
	v_cndmask_b32_e64 v9, 0, v33, s[56:57]
	v_cndmask_b32_e64 v8, 0, v32, s[56:57]
	v_pk_fma_f32 v[118:119], v[146:147], v[118:119], v[6:7]
	v_pk_fma_f32 v[8:9], v[8:9], v[98:99], v[4:5]
	v_lshlrev_b32_e32 v98, 16, v105
	v_lshlrev_b32_e32 v146, 16, v104
	v_and_b32_e32 v99, 0xffff0000, v105
	v_and_b32_e32 v147, 0xffff0000, v104
	v_cndmask_b32_e64 v105, 0, v43, s[54:55]
	v_cndmask_b32_e64 v104, 0, v42, s[54:55]
	v_pk_fma_f32 v[8:9], v[148:149], v[146:147], v[8:9]
	v_pk_fma_f32 v[98:99], v[104:105], v[98:99], v[118:119]
	v_lshlrev_b32_e32 v104, 16, v114
	v_lshlrev_b32_e32 v118, 16, v115
	v_and_b32_e32 v105, 0xffff0000, v114
	v_and_b32_e32 v119, 0xffff0000, v115
	v_cndmask_b32_e64 v115, 0, v69, s[52:53]
	v_cndmask_b32_e64 v114, 0, v68, s[52:53]
	v_cndmask_b32_e64 v147, 0, v71, s[52:53]
	v_cndmask_b32_e64 v146, 0, v70, s[52:53]
	v_pk_fma_f32 v[98:99], v[146:147], v[118:119], v[98:99]
	v_pk_fma_f32 v[8:9], v[114:115], v[104:105], v[8:9]
	v_lshlrev_b32_e32 v104, 16, v127
	v_lshlrev_b32_e32 v114, 16, v126
	v_and_b32_e32 v105, 0xffff0000, v127
	v_and_b32_e32 v115, 0xffff0000, v126
	v_pk_fma_f32 v[114:115], v[82:83], v[114:115], v[8:9]
	v_pk_fma_f32 v[98:99], v[72:73], v[104:105], v[98:99]
	v_cvt_pk_bf16_f32 v8, v114, v115
	v_cvt_pk_bf16_f32 v9, v98, v99
	ds_write2_b32 v124, v98, v99 offset0:2 offset1:3
	ds_write2_b32 v124, v114, v115 offset1:1
	v_lshlrev_b32_e32 v98, 16, v10
	v_lshlrev_b32_e32 v104, 16, v11
	v_and_b32_e32 v99, 0xffff0000, v10
	v_and_b32_e32 v105, 0xffff0000, v11
	v_cndmask_b32_e64 v11, 0, v25, s[56:57]
	v_cndmask_b32_e64 v10, 0, v24, s[56:57]
	v_cndmask_b32_e64 v115, 0, v27, s[56:57]
	v_cndmask_b32_e64 v114, 0, v26, s[56:57]
	v_pk_fma_f32 v[104:105], v[114:115], v[104:105], v[22:23]
	v_pk_fma_f32 v[10:11], v[10:11], v[98:99], v[20:21]
	v_lshlrev_b32_e32 v98, 16, v107
	v_lshlrev_b32_e32 v114, 16, v106
	v_and_b32_e32 v99, 0xffff0000, v107
	v_and_b32_e32 v115, 0xffff0000, v106
	v_cndmask_b32_e64 v107, 0, v31, s[54:55]
	v_cndmask_b32_e64 v106, 0, v30, s[54:55]
	v_cndmask_b32_e64 v119, 0, v29, s[54:55]
	v_cndmask_b32_e64 v118, 0, v28, s[54:55]
	v_pk_fma_f32 v[10:11], v[118:119], v[114:115], v[10:11]
	v_pk_fma_f32 v[98:99], v[106:107], v[98:99], v[104:105]
	v_lshlrev_b32_e32 v104, 16, v116
	v_lshlrev_b32_e32 v106, 16, v117
	v_and_b32_e32 v105, 0xffff0000, v116
	v_and_b32_e32 v107, 0xffff0000, v117
	v_cndmask_b32_e64 v115, 0, v37, s[52:53]
	v_cndmask_b32_e64 v114, 0, v36, s[52:53]
	v_cndmask_b32_e64 v117, 0, v39, s[52:53]
	v_cndmask_b32_e64 v116, 0, v38, s[52:53]
	v_pk_fma_f32 v[98:99], v[116:117], v[106:107], v[98:99]
	v_pk_fma_f32 v[10:11], v[114:115], v[104:105], v[10:11]
	v_lshlrev_b32_e32 v104, 16, v129
	v_and_b32_e32 v105, 0xffff0000, v129
	v_add_u32_e32 v118, s40, v137
	v_lshlrev_b32_e32 v106, 16, v128
	v_and_b32_e32 v107, 0xffff0000, v128
	v_pk_fma_f32 v[98:99], v[74:75], v[104:105], v[98:99]
	v_cmp_lt_i32_e64 s[46:47], -1, v118
	v_pk_fma_f32 v[106:107], v[84:85], v[106:107], v[10:11]
	v_cvt_pk_bf16_f32 v11, v98, v99
	ds_write2_b32 v124, v98, v99 offset0:6 offset1:7
	ds_write2_b32 v124, v106, v107 offset0:4 offset1:5
	v_cndmask_b32_e64 v98, 0, v118, s[46:47]
	v_add_u32_e32 v126, s27, v98
	v_cvt_pk_bf16_f32 v10, v106, v107
	v_mov_b32_dpp v104, v234 row_ror:3 row_mask:0xf bank_mask:0xf
	v_mov_b32_dpp v105, v235 row_ror:3 row_mask:0xf bank_mask:0xf
	v_mov_b32_dpp v106, v236 row_ror:3 row_mask:0xf bank_mask:0xf
; __device__ __forceinline__ void ld8bf(const bf16_t* p, float (&o)[8]) { unpack8(*(const u32x4*)p, o); }
; __device__ __forceinline__ bf16x8 pack_frag(const float (&v)[8]) { return __builtin_bit_cast(bf16x8, pack8(v)); }
; __device__ __forceinline__ void w_lru_m1(const Args& a, int l, unsigned char* ws, const bf16_t* proj, bf16_t* y, LAS unsigned char* wl, int b, int ck_, int h, int lane) {
;     ...
;         for (int tb = 0; tb < 4; ++tb) { const int tok = 16 * tb + lo, t = 64 * ck_ + tok; float s[8];
; #pragma unroll
;             for (int j = 0; j < 8; ++j) s[j] = bs[j];
; #pragma unroll
;             for (int k = 0; k < 4; ++k) { const int tt = t - 3 + k; float x[8];
;                 ld8bf(proj + (size_t)(b * SEQ + (tt >= 0 ? tt : 0)) * NIN + C_LX + ch0, x);
; #pragma unroll
;                 for (int j = 0; j < 8; ++j) s[j] += (tt >= 0 ? w[k][j] : 0.f) * x[j]; }
;             Xf[tb][kk] = pack_frag(s);
; #pragma unroll
;             for (int j = 0; j < 8; ++j) xcf[tok * 65 + 32 * kk + 8 * fq + j] = s[j]; }
	v_mov_b32_dpp v107, v237 row_ror:3 row_mask:0xf bank_mask:0xf
	v_mov_b32_dpp v104, v238 row_shr:3 row_mask:0xf bank_mask:0xf
	v_mov_b32_dpp v105, v239 row_shr:3 row_mask:0xf bank_mask:0xf
	v_mov_b32_dpp v106, v240 row_shr:3 row_mask:0xf bank_mask:0xf
	v_mov_b32_dpp v107, v241 row_shr:3 row_mask:0xf bank_mask:0xf
	v_max_i32_e32 v98, -1, v118
	v_add_u32_e32 v127, s80, v98
	v_mov_b32_dpp v114, v234 row_ror:2 row_mask:0xf bank_mask:0xf
	v_mov_b32_dpp v115, v235 row_ror:2 row_mask:0xf bank_mask:0xf
	v_mov_b32_dpp v116, v236 row_ror:2 row_mask:0xf bank_mask:0xf
	v_mov_b32_dpp v117, v237 row_ror:2 row_mask:0xf bank_mask:0xf
	v_mov_b32_dpp v114, v238 row_shr:2 row_mask:0xf bank_mask:0xf
	v_mov_b32_dpp v115, v239 row_shr:2 row_mask:0xf bank_mask:0xf
	v_mov_b32_dpp v116, v240 row_shr:2 row_mask:0xf bank_mask:0xf
	v_mov_b32_dpp v117, v241 row_shr:2 row_mask:0xf bank_mask:0xf
	v_max_i32_e32 v98, -2, v118
	v_add_u32_e32 v128, s81, v98
	v_mov_b32_dpp v146, v234 row_ror:1 row_mask:0xf bank_mask:0xf
	v_mov_b32_dpp v147, v235 row_ror:1 row_mask:0xf bank_mask:0xf
	v_mov_b32_dpp v148, v236 row_ror:1 row_mask:0xf bank_mask:0xf
	v_mov_b32_dpp v149, v237 row_ror:1 row_mask:0xf bank_mask:0xf
	v_mov_b32_dpp v146, v238 row_shr:1 row_mask:0xf bank_mask:0xf
	v_mov_b32_dpp v147, v239 row_shr:1 row_mask:0xf bank_mask:0xf
	v_mov_b32_dpp v148, v240 row_shr:1 row_mask:0xf bank_mask:0xf
	v_mov_b32_dpp v149, v241 row_shr:1 row_mask:0xf bank_mask:0xf
	v_or_b32_e32 v98, s20, v137
	v_cndmask_b32_e64 v98, 0, v98, s[42:43]
	v_add_u32_e32 v129, s27, v98
	v_mov_b64_e32 v[150:151], v[238:239]
	v_mov_b64_e32 v[152:153], v[240:241]
	v_mov_b32_e32 v80, 0x30c0
	v_cmp_lt_i32_e64 s[40:41], -2, v118
	v_mad_u32_u24 v138, v136, s76, v80
	v_cndmask_b32_e64 v33, 0, v33, s[46:47]
	v_cndmask_b32_e64 v32, 0, v32, s[46:47]
	v_cndmask_b32_e64 v35, 0, v35, s[46:47]
	v_cndmask_b32_e64 v34, 0, v34, s[46:47]
	v_cmp_lt_i32_e32 vcc, -3, v118
	v_cndmask_b32_e64 v43, 0, v43, s[40:41]
	v_cndmask_b32_e64 v42, 0, v42, s[40:41]
	v_cndmask_b32_e64 v41, 0, v41, s[40:41]
	v_cndmask_b32_e64 v40, 0, v40, s[40:41]
	v_add_u32_e32 v120, v95, v138
	v_cndmask_b32_e64 v25, 0, v25, s[46:47]
	v_cndmask_b32_e64 v24, 0, v24, s[46:47]
	v_cndmask_b32_e64 v27, 0, v27, s[46:47]
	v_cndmask_b32_e64 v26, 0, v26, s[46:47]
	v_cndmask_b32_e64 v29, 0, v29, s[40:41]
	v_cndmask_b32_e64 v28, 0, v28, s[40:41]
	s_mov_b64 s[80:81], 0x1080
	s_waitcnt vmcnt(0) lgkmcnt(0)
	v_lshlrev_b32_e32 v80, 16, v104
	v_lshlrev_b32_e32 v98, 16, v105
	v_and_b32_e32 v81, 0xffff0000, v104
	v_and_b32_e32 v99, 0xffff0000, v105
	v_pk_fma_f32 v[6:7], v[34:35], v[98:99], v[6:7]
	v_pk_fma_f32 v[4:5], v[32:33], v[80:81], v[4:5]
	v_lshlrev_b32_e32 v32, 16, v115
	v_lshlrev_b32_e32 v34, 16, v114
	v_and_b32_e32 v33, 0xffff0000, v115
	v_and_b32_e32 v35, 0xffff0000, v114
	v_pk_fma_f32 v[4:5], v[40:41], v[34:35], v[4:5]
	v_pk_fma_f32 v[6:7], v[42:43], v[32:33], v[6:7]
	v_lshlrev_b32_e32 v32, 16, v146
	v_lshlrev_b32_e32 v34, 16, v147
	v_and_b32_e32 v33, 0xffff0000, v146
	v_and_b32_e32 v35, 0xffff0000, v147
	v_cndmask_b32_e32 v41, 0, v69, vcc
	v_cndmask_b32_e32 v40, 0, v68, vcc
	v_cndmask_b32_e32 v43, 0, v71, vcc
	v_cndmask_b32_e32 v42, 0, v70, vcc
	v_pk_fma_f32 v[6:7], v[42:43], v[34:35], v[6:7]
	v_pk_fma_f32 v[4:5], v[40:41], v[32:33], v[4:5]
	v_lshlrev_b32_e32 v32, 16, v151
	v_and_b32_e32 v33, 0xffff0000, v151
	v_lshlrev_b32_e32 v34, 16, v150
	v_and_b32_e32 v35, 0xffff0000, v150
	v_pk_fma_f32 v[6:7], v[72:73], v[32:33], v[6:7]
	v_pk_fma_f32 v[34:35], v[82:83], v[34:35], v[4:5]
	v_cvt_pk_bf16_f32 v5, v6, v7
	ds_write2_b32 v120, v6, v7 offset0:2 offset1:3
	ds_write2_b32 v120, v34, v35 offset1:1
	v_lshlrev_b32_e32 v6, 16, v106
	v_lshlrev_b32_e32 v32, 16, v107
	v_and_b32_e32 v7, 0xffff0000, v106
	v_and_b32_e32 v33, 0xffff0000, v107
	v_pk_fma_f32 v[22:23], v[26:27], v[32:33], v[22:23]
	v_pk_fma_f32 v[6:7], v[24:25], v[6:7], v[20:21]
	v_lshlrev_b32_e32 v20, 16, v117
	v_lshlrev_b32_e32 v24, 16, v116
	v_and_b32_e32 v21, 0xffff0000, v117
	v_and_b32_e32 v25, 0xffff0000, v116
	v_cndmask_b32_e64 v27, 0, v31, s[40:41]
	v_cndmask_b32_e64 v26, 0, v30, s[40:41]
	v_pk_fma_f32 v[6:7], v[28:29], v[24:25], v[6:7]
	v_pk_fma_f32 v[20:21], v[26:27], v[20:21], v[22:23]
	v_lshlrev_b32_e32 v22, 16, v148
	v_lshlrev_b32_e32 v24, 16, v149
	v_and_b32_e32 v23, 0xffff0000, v148
	v_and_b32_e32 v25, 0xffff0000, v149
	v_cndmask_b32_e32 v27, 0, v37, vcc
	v_cndmask_b32_e32 v26, 0, v36, vcc
	v_cndmask_b32_e32 v29, 0, v39, vcc
	v_cndmask_b32_e32 v28, 0, v38, vcc
	v_pk_fma_f32 v[20:21], v[28:29], v[24:25], v[20:21]
	v_pk_fma_f32 v[6:7], v[26:27], v[22:23], v[6:7]
	v_lshlrev_b32_e32 v22, 16, v153
	v_and_b32_e32 v23, 0xffff0000, v153
	v_lshlrev_b32_e32 v24, 16, v152
	v_and_b32_e32 v25, 0xffff0000, v152
	v_pk_fma_f32 v[20:21], v[74:75], v[22:23], v[20:21]
	v_pk_fma_f32 v[24:25], v[84:85], v[24:25], v[6:7]
	v_cvt_pk_bf16_f32 v7, v20, v21
	ds_write2_b32 v120, v20, v21 offset0:6 offset1:7
	ds_write2_b32 v120, v24, v25 offset0:4 offset1:5
	v_add_u32_e32 v20, 32, v78
	v_ashrrev_i32_e32 v21, 31, v20
	v_lshl_add_u64 v[84:85], v[86:87], 0, s[80:81]
	s_mov_b64 s[80:81], 0x1880
	v_lshl_add_u64 v[106:107], v[86:87], 0, s[80:81]
	v_lshlrev_b64 v[104:105], 1, v[20:21]
	v_mov_b32_dpp v80, v242 row_ror:3 row_mask:0xf bank_mask:0xf
	v_mov_b32_dpp v81, v243 row_ror:3 row_mask:0xf bank_mask:0xf
	v_mov_b32_dpp v82, v244 row_ror:3 row_mask:0xf bank_mask:0xf
	v_mov_b32_dpp v83, v245 row_ror:3 row_mask:0xf bank_mask:0xf
	v_mov_b32_dpp v80, v246 row_shr:3 row_mask:0xf bank_mask:0xf
	v_mov_b32_dpp v81, v247 row_shr:3 row_mask:0xf bank_mask:0xf
	v_mov_b32_dpp v82, v248 row_shr:3 row_mask:0xf bank_mask:0xf
; __device__ __forceinline__ void ld8bf(const bf16_t* p, float (&o)[8]) { unpack8(*(const u32x4*)p, o); }
; __device__ __forceinline__ bf16x8 pack_frag(const float (&v)[8]) { return __builtin_bit_cast(bf16x8, pack8(v)); }
; __device__ __forceinline__ void w_lru_m1(const Args& a, int l, unsigned char* ws, const bf16_t* proj, bf16_t* y, LAS unsigned char* wl, int b, int ck_, int h, int lane) {
;     ...
;     for (int kk = 0; kk < 2; ++kk) { const int ch0 = 64 * h + 32 * kk + 8 * fq; float w[4][8], bs[8];
; #pragma unroll
;         for (int j = 0; j < 8; ++j) { bs[j] = cbias[ch0 + j];
; #pragma unroll
;             for (int k = 0; k < 4; ++k) w[k][j] = cw[k * 512 + ch0 + j]; }
; #pragma unroll
;         for (int tb = 0; tb < 4; ++tb) { const int tok = 16 * tb + lo, t = 64 * ck_ + tok; float s[8];
; #pragma unroll
;             for (int j = 0; j < 8; ++j) s[j] = bs[j];
; #pragma unroll
;             for (int k = 0; k < 4; ++k) { const int tt = t - 3 + k; float x[8];
;                 ld8bf(proj + (size_t)(b * SEQ + (tt >= 0 ? tt : 0)) * NIN + C_LX + ch0, x);
; #pragma unroll
;                 for (int j = 0; j < 8; ++j) s[j] += (tt >= 0 ? w[k][j] : 0.f) * x[j]; }
;             Xf[tb][kk] = pack_frag(s);
; #pragma unroll
;             for (int j = 0; j < 8; ++j) xcf[tok * 65 + 32 * kk + 8 * fq + j] = s[j]; }
	v_mov_b32_dpp v83, v249 row_shr:3 row_mask:0xf bank_mask:0xf
	v_cvt_pk_bf16_f32 v4, v34, v35
	v_mov_b32_dpp v32, v242 row_ror:2 row_mask:0xf bank_mask:0xf
	v_mov_b32_dpp v33, v243 row_ror:2 row_mask:0xf bank_mask:0xf
	v_mov_b32_dpp v34, v244 row_ror:2 row_mask:0xf bank_mask:0xf
	v_mov_b32_dpp v35, v245 row_ror:2 row_mask:0xf bank_mask:0xf
	v_mov_b32_dpp v32, v246 row_shr:2 row_mask:0xf bank_mask:0xf
	v_mov_b32_dpp v33, v247 row_shr:2 row_mask:0xf bank_mask:0xf
	v_mov_b32_dpp v34, v248 row_shr:2 row_mask:0xf bank_mask:0xf
	v_mov_b32_dpp v35, v249 row_shr:2 row_mask:0xf bank_mask:0xf
	v_mov_b32_dpp v28, v242 row_ror:1 row_mask:0xf bank_mask:0xf
	v_mov_b32_dpp v29, v243 row_ror:1 row_mask:0xf bank_mask:0xf
	v_mov_b32_dpp v30, v244 row_ror:1 row_mask:0xf bank_mask:0xf
	v_mov_b32_dpp v31, v245 row_ror:1 row_mask:0xf bank_mask:0xf
	v_mov_b32_dpp v28, v246 row_shr:1 row_mask:0xf bank_mask:0xf
	v_mov_b32_dpp v29, v247 row_shr:1 row_mask:0xf bank_mask:0xf
	v_mov_b32_dpp v30, v248 row_shr:1 row_mask:0xf bank_mask:0xf
	v_mov_b32_dpp v31, v249 row_shr:1 row_mask:0xf bank_mask:0xf
	v_cvt_pk_bf16_f32 v6, v24, v25
	v_mov_b64_e32 v[24:25], v[246:247]
	v_mov_b64_e32 v[26:27], v[248:249]
	ds_read_b128 v[40:43], v199 offset:17808
	ds_read_b128 v[72:75], v199 offset:17792
	ds_read_b128 v[68:71], v199 offset:16784
	s_nop 0
	ds_read_b128 v[76:79], v199 offset:16768
	ds_read_b128 v[36:39], v199 offset:17040
	ds_read_b128 v[20:23], v199 offset:17024
	ds_read_b128 v[92:95], v199 offset:17280
	s_nop 0
	ds_read_b128 v[84:87], v199 offset:17296
	s_nop 0
	ds_read_b128 v[96:99], v199 offset:17536
	s_nop 0
	ds_read_b128 v[146:149], v199 offset:17552
	s_waitcnt vmcnt(0) lgkmcnt(0)
	v_lshlrev_b32_e32 v106, 16, v80
	v_lshlrev_b32_e32 v114, 16, v81
	v_and_b32_e32 v107, 0xffff0000, v80
	v_and_b32_e32 v115, 0xffff0000, v81
	v_cndmask_b32_e64 v81, 0, v77, s[50:51]
	v_cndmask_b32_e64 v80, 0, v76, s[50:51]
	v_cndmask_b32_e64 v117, 0, v79, s[50:51]
	v_cndmask_b32_e64 v116, 0, v78, s[50:51]
	v_pk_fma_f32 v[114:115], v[116:117], v[114:115], v[74:75]
	v_pk_fma_f32 v[80:81], v[80:81], v[106:107], v[72:73]
	v_lshlrev_b32_e32 v106, 16, v33
	v_lshlrev_b32_e32 v116, 16, v32
	v_and_b32_e32 v107, 0xffff0000, v33
	v_and_b32_e32 v117, 0xffff0000, v32
	v_cndmask_b32_e64 v33, 0, v23, s[48:49]
	v_cndmask_b32_e64 v32, 0, v22, s[48:49]
	v_cndmask_b32_e64 v119, 0, v21, s[48:49]
	v_cndmask_b32_e64 v118, 0, v20, s[48:49]
	v_pk_fma_f32 v[80:81], v[118:119], v[116:117], v[80:81]
	v_pk_fma_f32 v[32:33], v[32:33], v[106:107], v[114:115]
	v_lshlrev_b32_e32 v106, 16, v28
	v_lshlrev_b32_e32 v114, 16, v29
	v_and_b32_e32 v107, 0xffff0000, v28
	v_and_b32_e32 v115, 0xffff0000, v29
	v_cndmask_b32_e64 v29, 0, v93, s[44:45]
	v_cndmask_b32_e64 v28, 0, v92, s[44:45]
	v_cndmask_b32_e64 v117, 0, v95, s[44:45]
	v_cndmask_b32_e64 v116, 0, v94, s[44:45]
	v_pk_fma_f32 v[32:33], v[116:117], v[114:115], v[32:33]
	v_pk_fma_f32 v[28:29], v[28:29], v[106:107], v[80:81]
	v_lshlrev_b32_e32 v80, 16, v25
	v_lshlrev_b32_e32 v116, 16, v24
	v_and_b32_e32 v81, 0xffff0000, v25
	v_and_b32_e32 v117, 0xffff0000, v24
	v_cndmask_b32_e64 v107, 0, v99, s[42:43]
	v_cndmask_b32_e64 v106, 0, v98, s[42:43]
	v_cndmask_b32_e64 v115, 0, v97, s[42:43]
	v_cndmask_b32_e64 v114, 0, v96, s[42:43]
	v_pk_fma_f32 v[24:25], v[114:115], v[116:117], v[28:29]
	v_pk_fma_f32 v[28:29], v[106:107], v[80:81], v[32:33]
	v_cvt_pk_bf16_f32 v32, v24, v25
	v_cvt_pk_bf16_f32 v33, v28, v29
	ds_write2_b32 v121, v28, v29 offset0:34 offset1:35
	ds_write2_b32 v121, v24, v25 offset0:32 offset1:33
	v_lshlrev_b32_e32 v24, 16, v82
	v_lshlrev_b32_e32 v28, 16, v83
	v_and_b32_e32 v25, 0xffff0000, v82
	v_and_b32_e32 v29, 0xffff0000, v83
	v_cndmask_b32_e64 v81, 0, v69, s[50:51]
	v_cndmask_b32_e64 v80, 0, v68, s[50:51]
	v_cndmask_b32_e64 v83, 0, v71, s[50:51]
	v_cndmask_b32_e64 v82, 0, v70, s[50:51]
	v_pk_fma_f32 v[28:29], v[82:83], v[28:29], v[42:43]
	v_pk_fma_f32 v[24:25], v[80:81], v[24:25], v[40:41]
	v_lshlrev_b32_e32 v80, 16, v35
	v_lshlrev_b32_e32 v82, 16, v34
	v_and_b32_e32 v81, 0xffff0000, v35
	v_and_b32_e32 v83, 0xffff0000, v34
	v_cndmask_b32_e64 v35, 0, v39, s[48:49]
	v_cndmask_b32_e64 v34, 0, v38, s[48:49]
	v_cndmask_b32_e64 v97, 0, v37, s[48:49]
	v_cndmask_b32_e64 v96, 0, v36, s[48:49]
	v_pk_fma_f32 v[24:25], v[96:97], v[82:83], v[24:25]
	v_pk_fma_f32 v[28:29], v[34:35], v[80:81], v[28:29]
	v_lshlrev_b32_e32 v34, 16, v30
	v_lshlrev_b32_e32 v80, 16, v31
	v_and_b32_e32 v35, 0xffff0000, v30
	v_and_b32_e32 v81, 0xffff0000, v31
	v_cndmask_b32_e64 v31, 0, v85, s[44:45]
	v_cndmask_b32_e64 v30, 0, v84, s[44:45]
	v_cndmask_b32_e64 v83, 0, v87, s[44:45]
	v_cndmask_b32_e64 v82, 0, v86, s[44:45]
	v_pk_fma_f32 v[28:29], v[82:83], v[80:81], v[28:29]
	v_pk_fma_f32 v[24:25], v[30:31], v[34:35], v[24:25]
	v_lshlrev_b32_e32 v30, 16, v27
	v_lshlrev_b32_e32 v34, 16, v26
	v_and_b32_e32 v31, 0xffff0000, v27
	v_and_b32_e32 v35, 0xffff0000, v26
	v_cndmask_b32_e64 v117, 0, v149, s[42:43]
	v_cndmask_b32_e64 v116, 0, v148, s[42:43]
	v_cndmask_b32_e64 v119, 0, v147, s[42:43]
	v_cndmask_b32_e64 v118, 0, v146, s[42:43]
	v_pk_fma_f32 v[24:25], v[118:119], v[34:35], v[24:25]
	v_pk_fma_f32 v[26:27], v[116:117], v[30:31], v[28:29]
	v_cvt_pk_bf16_f32 v34, v24, v25
	ds_write2_b32 v121, v26, v27 offset0:38 offset1:39
	ds_write2_b32 v121, v24, v25 offset0:36 offset1:37
	v_cvt_pk_bf16_f32 v35, v26, v27
	v_mov_b32_dpp v24, v246 row_ror:3 row_mask:0xf bank_mask:0xf
	v_mov_b32_dpp v25, v247 row_ror:3 row_mask:0xf bank_mask:0xf
	v_mov_b32_dpp v26, v248 row_ror:3 row_mask:0xf bank_mask:0xf
	v_mov_b32_dpp v27, v249 row_ror:3 row_mask:0xf bank_mask:0xf
	v_mov_b32_dpp v24, v250 row_shr:3 row_mask:0xf bank_mask:0xf
; __device__ __forceinline__ void ld8bf(const bf16_t* p, float (&o)[8]) { unpack8(*(const u32x4*)p, o); }
; __device__ __forceinline__ bf16x8 pack_frag(const float (&v)[8]) { return __builtin_bit_cast(bf16x8, pack8(v)); }
; __device__ __forceinline__ void w_lru_m1(const Args& a, int l, unsigned char* ws, const bf16_t* proj, bf16_t* y, LAS unsigned char* wl, int b, int ck_, int h, int lane) {
;     ...
;         for (int tb = 0; tb < 4; ++tb) { const int tok = 16 * tb + lo, t = 64 * ck_ + tok; float s[8];
; #pragma unroll
;             for (int j = 0; j < 8; ++j) s[j] = bs[j];
; #pragma unroll
;             for (int k = 0; k < 4; ++k) { const int tt = t - 3 + k; float x[8];
;                 ld8bf(proj + (size_t)(b * SEQ + (tt >= 0 ? tt : 0)) * NIN + C_LX + ch0, x);
; #pragma unroll
;                 for (int j = 0; j < 8; ++j) s[j] += (tt >= 0 ? w[k][j] : 0.f) * x[j]; }
;             Xf[tb][kk] = pack_frag(s);
; #pragma unroll
;             for (int j = 0; j < 8; ++j) xcf[tok * 65 + 32 * kk + 8 * fq + j] = s[j]; }
	v_mov_b32_dpp v25, v251 row_shr:3 row_mask:0xf bank_mask:0xf
	v_mov_b32_dpp v26, v252 row_shr:3 row_mask:0xf bank_mask:0xf
	v_mov_b32_dpp v27, v253 row_shr:3 row_mask:0xf bank_mask:0xf
	v_mov_b32_dpp v28, v246 row_ror:2 row_mask:0xf bank_mask:0xf
	v_mov_b32_dpp v29, v247 row_ror:2 row_mask:0xf bank_mask:0xf
	v_mov_b32_dpp v30, v248 row_ror:2 row_mask:0xf bank_mask:0xf
	v_mov_b32_dpp v31, v249 row_ror:2 row_mask:0xf bank_mask:0xf
	v_mov_b32_dpp v28, v250 row_shr:2 row_mask:0xf bank_mask:0xf
	v_mov_b32_dpp v29, v251 row_shr:2 row_mask:0xf bank_mask:0xf
	v_mov_b32_dpp v30, v252 row_shr:2 row_mask:0xf bank_mask:0xf
	v_mov_b32_dpp v31, v253 row_shr:2 row_mask:0xf bank_mask:0xf
	v_mov_b32_dpp v80, v246 row_ror:1 row_mask:0xf bank_mask:0xf
	v_mov_b32_dpp v81, v247 row_ror:1 row_mask:0xf bank_mask:0xf
	v_mov_b32_dpp v82, v248 row_ror:1 row_mask:0xf bank_mask:0xf
	v_mov_b32_dpp v83, v249 row_ror:1 row_mask:0xf bank_mask:0xf
	v_mov_b32_dpp v80, v250 row_shr:1 row_mask:0xf bank_mask:0xf
	v_mov_b32_dpp v81, v251 row_shr:1 row_mask:0xf bank_mask:0xf
	v_mov_b32_dpp v82, v252 row_shr:1 row_mask:0xf bank_mask:0xf
	v_mov_b32_dpp v83, v253 row_shr:1 row_mask:0xf bank_mask:0xf
	v_mov_b64_e32 v[96:97], v[250:251]
	v_mov_b64_e32 v[98:99], v[252:253]
	v_cndmask_b32_e64 v147, 0, v79, s[62:63]
	v_cndmask_b32_e64 v146, 0, v78, s[62:63]
	v_cndmask_b32_e64 v149, 0, v21, s[60:61]
	v_cndmask_b32_e64 v148, 0, v20, s[60:61]
	s_add_i32 s48, s20, s27
	s_lshl_b32 s20, s91, 7
	s_add_u32 s44, s10, s20
	s_addc_u32 s45, s11, 0
	s_waitcnt vmcnt(0) lgkmcnt(0)
	v_lshlrev_b32_e32 v134, 16, v24
	v_lshlrev_b32_e32 v142, 16, v25
	v_and_b32_e32 v135, 0xffff0000, v24
	v_and_b32_e32 v143, 0xffff0000, v25
	v_cndmask_b32_e64 v25, 0, v77, s[62:63]
	v_cndmask_b32_e64 v24, 0, v76, s[62:63]
	v_pk_fma_f32 v[142:143], v[146:147], v[142:143], v[74:75]
	v_pk_fma_f32 v[24:25], v[24:25], v[134:135], v[72:73]
	v_lshlrev_b32_e32 v134, 16, v29
	v_lshlrev_b32_e32 v146, 16, v28
	v_and_b32_e32 v135, 0xffff0000, v29
	v_and_b32_e32 v147, 0xffff0000, v28
	v_cndmask_b32_e64 v29, 0, v23, s[60:61]
	v_cndmask_b32_e64 v28, 0, v22, s[60:61]
	v_pk_fma_f32 v[24:25], v[148:149], v[146:147], v[24:25]
	v_pk_fma_f32 v[28:29], v[28:29], v[134:135], v[142:143]
	v_lshlrev_b32_e32 v134, 16, v80
	v_lshlrev_b32_e32 v142, 16, v81
	v_and_b32_e32 v135, 0xffff0000, v80
	v_and_b32_e32 v143, 0xffff0000, v81
	v_cndmask_b32_e64 v81, 0, v93, s[58:59]
	v_cndmask_b32_e64 v80, 0, v92, s[58:59]
	v_cndmask_b32_e64 v147, 0, v95, s[58:59]
	v_cndmask_b32_e64 v146, 0, v94, s[58:59]
	v_pk_fma_f32 v[28:29], v[146:147], v[142:143], v[28:29]
	v_pk_fma_f32 v[24:25], v[80:81], v[134:135], v[24:25]
	v_lshlrev_b32_e32 v80, 16, v97
	v_lshlrev_b32_e32 v134, 16, v96
	v_and_b32_e32 v81, 0xffff0000, v97
	v_and_b32_e32 v135, 0xffff0000, v96
	v_pk_fma_f32 v[24:25], v[114:115], v[134:135], v[24:25]
	v_pk_fma_f32 v[80:81], v[106:107], v[80:81], v[28:29]
	v_cvt_pk_bf16_f32 v28, v24, v25
	v_cvt_pk_bf16_f32 v29, v80, v81
	ds_write2_b32 v125, v80, v81 offset0:34 offset1:35
	ds_write2_b32 v125, v24, v25 offset0:32 offset1:33
	v_lshlrev_b32_e32 v24, 16, v26
	v_lshlrev_b32_e32 v80, 16, v27
	v_and_b32_e32 v25, 0xffff0000, v26
	v_and_b32_e32 v81, 0xffff0000, v27
	v_cndmask_b32_e64 v27, 0, v69, s[62:63]
	v_cndmask_b32_e64 v26, 0, v68, s[62:63]
	v_cndmask_b32_e64 v97, 0, v71, s[62:63]
	v_cndmask_b32_e64 v96, 0, v70, s[62:63]
	v_pk_fma_f32 v[80:81], v[96:97], v[80:81], v[42:43]
	v_pk_fma_f32 v[24:25], v[26:27], v[24:25], v[40:41]
	v_lshlrev_b32_e32 v26, 16, v31
	v_lshlrev_b32_e32 v96, 16, v30
	v_and_b32_e32 v27, 0xffff0000, v31
	v_and_b32_e32 v97, 0xffff0000, v30
	v_cndmask_b32_e64 v31, 0, v39, s[60:61]
	v_cndmask_b32_e64 v30, 0, v38, s[60:61]
	v_cndmask_b32_e64 v135, 0, v37, s[60:61]
	v_cndmask_b32_e64 v134, 0, v36, s[60:61]
	v_pk_fma_f32 v[24:25], v[134:135], v[96:97], v[24:25]
	v_pk_fma_f32 v[26:27], v[30:31], v[26:27], v[80:81]
	v_lshlrev_b32_e32 v30, 16, v82
	v_lshlrev_b32_e32 v80, 16, v83
	v_and_b32_e32 v31, 0xffff0000, v82
	v_and_b32_e32 v81, 0xffff0000, v83
	v_cndmask_b32_e64 v83, 0, v85, s[58:59]
	v_cndmask_b32_e64 v82, 0, v84, s[58:59]
	v_cndmask_b32_e64 v97, 0, v87, s[58:59]
	v_cndmask_b32_e64 v96, 0, v86, s[58:59]
	v_pk_fma_f32 v[26:27], v[96:97], v[80:81], v[26:27]
	v_pk_fma_f32 v[24:25], v[82:83], v[30:31], v[24:25]
	v_lshlrev_b32_e32 v30, 16, v99
	v_lshlrev_b32_e32 v80, 16, v98
	v_and_b32_e32 v31, 0xffff0000, v99
	v_and_b32_e32 v81, 0xffff0000, v98
	v_pk_fma_f32 v[24:25], v[118:119], v[80:81], v[24:25]
	v_pk_fma_f32 v[26:27], v[116:117], v[30:31], v[26:27]
	v_cvt_pk_bf16_f32 v30, v24, v25
	ds_write2_b32 v125, v26, v27 offset0:38 offset1:39
	ds_write2_b32 v125, v24, v25 offset0:36 offset1:37
	v_cvt_pk_bf16_f32 v31, v26, v27
	v_mov_b32_dpp v24, v250 row_ror:3 row_mask:0xf bank_mask:0xf
	v_mov_b32_dpp v25, v251 row_ror:3 row_mask:0xf bank_mask:0xf
	v_mov_b32_dpp v26, v252 row_ror:3 row_mask:0xf bank_mask:0xf
	v_mov_b32_dpp v27, v253 row_ror:3 row_mask:0xf bank_mask:0xf
	v_mov_b32_dpp v24, v190 row_shr:3 row_mask:0xf bank_mask:0xf
	v_mov_b32_dpp v25, v191 row_shr:3 row_mask:0xf bank_mask:0xf
	v_mov_b32_dpp v26, v192 row_shr:3 row_mask:0xf bank_mask:0xf
	v_mov_b32_dpp v27, v193 row_shr:3 row_mask:0xf bank_mask:0xf
	v_mov_b32_dpp v80, v250 row_ror:2 row_mask:0xf bank_mask:0xf
	v_mov_b32_dpp v81, v251 row_ror:2 row_mask:0xf bank_mask:0xf
	v_mov_b32_dpp v82, v252 row_ror:2 row_mask:0xf bank_mask:0xf
	v_mov_b32_dpp v83, v253 row_ror:2 row_mask:0xf bank_mask:0xf
	v_mov_b32_dpp v80, v190 row_shr:2 row_mask:0xf bank_mask:0xf
	v_mov_b32_dpp v81, v191 row_shr:2 row_mask:0xf bank_mask:0xf
	v_mov_b32_dpp v82, v192 row_shr:2 row_mask:0xf bank_mask:0xf
	v_mov_b32_dpp v83, v193 row_shr:2 row_mask:0xf bank_mask:0xf
	v_mov_b32_dpp v96, v250 row_ror:1 row_mask:0xf bank_mask:0xf
	v_mov_b32_dpp v97, v251 row_ror:1 row_mask:0xf bank_mask:0xf
	v_mov_b32_dpp v98, v252 row_ror:1 row_mask:0xf bank_mask:0xf
	v_mov_b32_dpp v99, v253 row_ror:1 row_mask:0xf bank_mask:0xf
	v_mov_b32_dpp v96, v190 row_shr:1 row_mask:0xf bank_mask:0xf
	v_mov_b32_dpp v97, v191 row_shr:1 row_mask:0xf bank_mask:0xf
	v_mov_b32_dpp v98, v192 row_shr:1 row_mask:0xf bank_mask:0xf
	v_mov_b32_dpp v99, v193 row_shr:1 row_mask:0xf bank_mask:0xf
	v_mov_b64_e32 v[130:131], v[190:191]
	v_mov_b64_e32 v[132:133], v[192:193]
	v_cndmask_b32_e64 v147, 0, v79, s[56:57]
	v_cndmask_b32_e64 v146, 0, v78, s[56:57]
	v_cndmask_b32_e64 v149, 0, v21, s[54:55]
	v_cndmask_b32_e64 v148, 0, v20, s[54:55]
	v_cndmask_b32_e64 v79, 0, v79, s[46:47]
	v_cndmask_b32_e64 v78, 0, v78, s[46:47]
	v_cndmask_b32_e64 v21, 0, v21, s[40:41]
	v_cndmask_b32_e64 v20, 0, v20, s[40:41]
	s_waitcnt vmcnt(0) lgkmcnt(0)
; __device__ __forceinline__ void ld8bf(const bf16_t* p, float (&o)[8]) { unpack8(*(const u32x4*)p, o); }
; __device__ __forceinline__ bf16x8 pack_frag(const float (&v)[8]) { return __builtin_bit_cast(bf16x8, pack8(v)); }
; __device__ __forceinline__ void w_lru_m1(const Args& a, int l, unsigned char* ws, const bf16_t* proj, bf16_t* y, LAS unsigned char* wl, int b, int ck_, int h, int lane) {
;     ...
;         for (int tb = 0; tb < 4; ++tb) { const int tok = 16 * tb + lo, t = 64 * ck_ + tok; float s[8];
; #pragma unroll
;             for (int j = 0; j < 8; ++j) s[j] = bs[j];
; #pragma unroll
;             for (int k = 0; k < 4; ++k) { const int tt = t - 3 + k; float x[8];
;                 ld8bf(proj + (size_t)(b * SEQ + (tt >= 0 ? tt : 0)) * NIN + C_LX + ch0, x);
; #pragma unroll
;                 for (int j = 0; j < 8; ++j) s[j] += (tt >= 0 ? w[k][j] : 0.f) * x[j]; }
;             Xf[tb][kk] = pack_frag(s);
; #pragma unroll
;             for (int j = 0; j < 8; ++j) xcf[tok * 65 + 32 * kk + 8 * fq + j] = s[j]; }
	v_lshlrev_b32_e32 v134, 16, v24
	v_lshlrev_b32_e32 v142, 16, v25
	v_and_b32_e32 v135, 0xffff0000, v24
	v_and_b32_e32 v143, 0xffff0000, v25
	v_cndmask_b32_e64 v25, 0, v77, s[56:57]
	v_cndmask_b32_e64 v24, 0, v76, s[56:57]
	v_pk_fma_f32 v[142:143], v[146:147], v[142:143], v[74:75]
	v_pk_fma_f32 v[24:25], v[24:25], v[134:135], v[72:73]
	v_lshlrev_b32_e32 v134, 16, v81
	v_lshlrev_b32_e32 v146, 16, v80
	v_and_b32_e32 v135, 0xffff0000, v81
	v_and_b32_e32 v147, 0xffff0000, v80
	v_cndmask_b32_e64 v81, 0, v23, s[54:55]
	v_cndmask_b32_e64 v80, 0, v22, s[54:55]
	v_pk_fma_f32 v[24:25], v[148:149], v[146:147], v[24:25]
	v_pk_fma_f32 v[80:81], v[80:81], v[134:135], v[142:143]
	v_lshlrev_b32_e32 v134, 16, v96
	v_lshlrev_b32_e32 v142, 16, v97
	v_and_b32_e32 v135, 0xffff0000, v96
	v_and_b32_e32 v143, 0xffff0000, v97
	v_cndmask_b32_e64 v97, 0, v93, s[52:53]
	v_cndmask_b32_e64 v96, 0, v92, s[52:53]
	v_cndmask_b32_e64 v147, 0, v95, s[52:53]
	v_cndmask_b32_e64 v146, 0, v94, s[52:53]
	v_pk_fma_f32 v[80:81], v[146:147], v[142:143], v[80:81]
	v_pk_fma_f32 v[24:25], v[96:97], v[134:135], v[24:25]
	v_lshlrev_b32_e32 v96, 16, v131
	v_lshlrev_b32_e32 v134, 16, v130
	v_and_b32_e32 v97, 0xffff0000, v131
	v_and_b32_e32 v135, 0xffff0000, v130
	v_pk_fma_f32 v[130:131], v[114:115], v[134:135], v[24:25]
	v_pk_fma_f32 v[80:81], v[106:107], v[96:97], v[80:81]
	v_cvt_pk_bf16_f32 v24, v130, v131
	v_cvt_pk_bf16_f32 v25, v80, v81
	ds_write2_b32 v124, v80, v81 offset0:34 offset1:35
	ds_write2_b32 v124, v130, v131 offset0:32 offset1:33
	v_lshlrev_b32_e32 v80, 16, v26
	v_lshlrev_b32_e32 v96, 16, v27
	v_and_b32_e32 v81, 0xffff0000, v26
	v_and_b32_e32 v97, 0xffff0000, v27
	v_cndmask_b32_e64 v27, 0, v69, s[56:57]
	v_cndmask_b32_e64 v26, 0, v68, s[56:57]
	v_cndmask_b32_e64 v131, 0, v71, s[56:57]
	v_cndmask_b32_e64 v130, 0, v70, s[56:57]
	v_pk_fma_f32 v[96:97], v[130:131], v[96:97], v[42:43]
	v_pk_fma_f32 v[26:27], v[26:27], v[80:81], v[40:41]
	v_lshlrev_b32_e32 v80, 16, v83
	v_lshlrev_b32_e32 v130, 16, v82
	v_and_b32_e32 v81, 0xffff0000, v83
	v_and_b32_e32 v131, 0xffff0000, v82
	v_cndmask_b32_e64 v83, 0, v39, s[54:55]
	v_cndmask_b32_e64 v82, 0, v38, s[54:55]
	v_cndmask_b32_e64 v135, 0, v37, s[54:55]
	v_cndmask_b32_e64 v134, 0, v36, s[54:55]
	v_pk_fma_f32 v[26:27], v[134:135], v[130:131], v[26:27]
	v_pk_fma_f32 v[80:81], v[82:83], v[80:81], v[96:97]
	v_lshlrev_b32_e32 v82, 16, v98
	v_lshlrev_b32_e32 v96, 16, v99
	v_and_b32_e32 v83, 0xffff0000, v98
	v_and_b32_e32 v97, 0xffff0000, v99
	v_cndmask_b32_e64 v99, 0, v85, s[52:53]
	v_cndmask_b32_e64 v98, 0, v84, s[52:53]
	v_cndmask_b32_e64 v131, 0, v87, s[52:53]
	v_cndmask_b32_e64 v130, 0, v86, s[52:53]
	v_pk_fma_f32 v[80:81], v[130:131], v[96:97], v[80:81]
	v_pk_fma_f32 v[26:27], v[98:99], v[82:83], v[26:27]
	v_lshlrev_b32_e32 v82, 16, v133
	v_and_b32_e32 v83, 0xffff0000, v133
	v_lshlrev_b32_e32 v96, 16, v132
	v_and_b32_e32 v97, 0xffff0000, v132
	v_pk_fma_f32 v[80:81], v[116:117], v[82:83], v[80:81]
	v_pk_fma_f32 v[96:97], v[118:119], v[96:97], v[26:27]
	v_cvt_pk_bf16_f32 v27, v80, v81
	ds_write2_b32 v124, v80, v81 offset0:38 offset1:39
	ds_write2_b32 v124, v96, v97 offset0:36 offset1:37
	v_mov_b32_dpp v130, v190 row_ror:3 row_mask:0xf bank_mask:0xf
	v_mov_b32_dpp v131, v191 row_ror:3 row_mask:0xf bank_mask:0xf
	v_mov_b32_dpp v132, v192 row_ror:3 row_mask:0xf bank_mask:0xf
	v_mov_b32_dpp v133, v193 row_ror:3 row_mask:0xf bank_mask:0xf
	v_mov_b32_dpp v130, v194 row_shr:3 row_mask:0xf bank_mask:0xf
	v_mov_b32_dpp v131, v195 row_shr:3 row_mask:0xf bank_mask:0xf
	v_mov_b32_dpp v132, v196 row_shr:3 row_mask:0xf bank_mask:0xf
	v_mov_b32_dpp v133, v197 row_shr:3 row_mask:0xf bank_mask:0xf
	v_mov_b32_dpp v124, v190 row_ror:2 row_mask:0xf bank_mask:0xf
	v_mov_b32_dpp v125, v191 row_ror:2 row_mask:0xf bank_mask:0xf
	v_mov_b32_dpp v126, v192 row_ror:2 row_mask:0xf bank_mask:0xf
	v_mov_b32_dpp v127, v193 row_ror:2 row_mask:0xf bank_mask:0xf
	v_mov_b32_dpp v124, v194 row_shr:2 row_mask:0xf bank_mask:0xf
	v_mov_b32_dpp v125, v195 row_shr:2 row_mask:0xf bank_mask:0xf
	v_mov_b32_dpp v126, v196 row_shr:2 row_mask:0xf bank_mask:0xf
	v_mov_b32_dpp v127, v197 row_shr:2 row_mask:0xf bank_mask:0xf
	v_cvt_pk_bf16_f32 v26, v96, v97
	v_mov_b32_dpp v96, v190 row_ror:1 row_mask:0xf bank_mask:0xf
	v_mov_b32_dpp v97, v191 row_ror:1 row_mask:0xf bank_mask:0xf
	v_mov_b32_dpp v98, v192 row_ror:1 row_mask:0xf bank_mask:0xf
	v_mov_b32_dpp v99, v193 row_ror:1 row_mask:0xf bank_mask:0xf
	v_mov_b32_dpp v96, v194 row_shr:1 row_mask:0xf bank_mask:0xf
	v_mov_b32_dpp v97, v195 row_shr:1 row_mask:0xf bank_mask:0xf
	v_mov_b32_dpp v98, v196 row_shr:1 row_mask:0xf bank_mask:0xf
	v_mov_b32_dpp v99, v197 row_shr:1 row_mask:0xf bank_mask:0xf
	v_mov_b64_e32 v[80:81], v[194:195]
	v_mov_b64_e32 v[82:83], v[196:197]
	v_cndmask_b32_e64 v77, 0, v77, s[46:47]
	v_cndmask_b32_e64 v76, 0, v76, s[46:47]
	v_cndmask_b32_e64 v23, 0, v23, s[40:41]
	v_cndmask_b32_e64 v22, 0, v22, s[40:41]
	v_cndmask_b32_e64 v69, 0, v69, s[46:47]
	v_cndmask_b32_e64 v68, 0, v68, s[46:47]
	v_cndmask_b32_e64 v71, 0, v71, s[46:47]
	v_cndmask_b32_e64 v70, 0, v70, s[46:47]
	v_cndmask_b32_e64 v39, 0, v39, s[40:41]
	v_cndmask_b32_e64 v38, 0, v38, s[40:41]
	v_cndmask_b32_e64 v37, 0, v37, s[40:41]
	v_cndmask_b32_e64 v36, 0, v36, s[40:41]
	s_add_u32 s46, s71, s20
	s_addc_u32 s47, s64, 0
	s_ashr_i32 s91, s90, 31
	s_lshl_b64 s[42:43], s[90:91], 9
	s_or_b32 s42, s42, s21
	s_waitcnt vmcnt(0) lgkmcnt(0)
; __device__ __forceinline__ void w_lru_m1(const Args& a, int l, unsigned char* ws, const bf16_t* proj, bf16_t* y, LAS unsigned char* wl, int b, int ck_, int h, int lane) {
;     ...
;         for (int tb = 0; tb < 4; ++tb) { const int tok = 16 * tb + lo, t = 64 * ck_ + tok; float s[8];
; #pragma unroll
;             for (int j = 0; j < 8; ++j) s[j] = bs[j];
; #pragma unroll
;             for (int k = 0; k < 4; ++k) { const int tt = t - 3 + k; float x[8];
;                 ld8bf(proj + (size_t)(b * SEQ + (tt >= 0 ? tt : 0)) * NIN + C_LX + ch0, x);
; #pragma unroll
;                 for (int j = 0; j < 8; ++j) s[j] += (tt >= 0 ? w[k][j] : 0.f) * x[j]; }
;             Xf[tb][kk] = pack_frag(s);
; #pragma unroll
;             for (int j = 0; j < 8; ++j) xcf[tok * 65 + 32 * kk + 8 * fq + j] = s[j]; }
;     }
;     WAVE_LDS_FENCE();
; #pragma unroll
;     for (int jb = 0; jb < 4; ++jb) {
;         bf16x8 WaF[2], WxF[2]; f32x4 pba, pbx, plam;
; #pragma unroll
;         for (int kk = 0; kk < 2; ++kk) { WaF[kk] = nWa[kk]; WxF[kk] = nWx[kk]; }
;         pba = nba; pbx = nbx; plam = nlam;
;         if (jb < 3) {
; #pragma unroll
;             for (int kk = 0; kk < 2; ++kk) { nWa[kk] = *(const bf16x8*)(waT + (16 * (jb + 1) + lo) * 64 + 32 * kk + 8 * fq); nWx[kk] = *(const bf16x8*)(wxT + (16 * (jb + 1) + lo) * 64 + 32 * kk + 8 * fq); }
;             nba = *(const f32x4*)(ba + 16 * (jb + 1) + 4 * fq); nbx = *(const f32x4*)(bx + 16 * (jb + 1) + 4 * fq); nlam = *(const f32x4*)(lam + 16 * (jb + 1) + 4 * fq);
;         }
;         const int j0 = 16 * jb + 4 * fq;
;         float bav[4], bxv[4], sp[4], hc[4], Pc[4];
; #pragma unroll
;         for (int r = 0; r < 4; ++r) { bav[r] = pba[r]; bxv[r] = pbx[r]; sp[r] = log1pf(__expf(-plam[r])); hc[r] = 0.f; Pc[r] = 1.f; }
; #pragma unroll
;         for (int tb = 0; tb < 4; ++tb) { const int tok = 16 * tb + lo;
;             f32x4 ga = {0.f, 0.f, 0.f, 0.f}, gx = {0.f, 0.f, 0.f, 0.f};
; #pragma unroll
;             for (int kk = 0; kk < 2; ++kk) { ga = __builtin_amdgcn_mfma_f32_16x16x32_bf16(WaF[kk], Xf[tb][kk], ga, 0, 0, 0); gx = __builtin_amdgcn_mfma_f32_16x16x32_bf16(WxF[kk], Xf[tb][kk], gx, 0, 0, 0); }
;             float hv[4], pv[4];
; #pragma unroll
;             for (int r = 0; r < 4; ++r) {
;                 const float rg = sigmoidf_(ga[r] + bav[r]), ig = sigmoidf_(gx[r] + bxv[r]);
	v_lshlrev_b32_e32 v102, 16, v130
	v_lshlrev_b32_e32 v104, 16, v131
	v_and_b32_e32 v103, 0xffff0000, v130
	v_and_b32_e32 v105, 0xffff0000, v131
	v_pk_fma_f32 v[74:75], v[78:79], v[104:105], v[74:75]
	v_pk_fma_f32 v[72:73], v[76:77], v[102:103], v[72:73]
	v_lshlrev_b32_e32 v76, 16, v125
	v_lshlrev_b32_e32 v78, 16, v124
	v_and_b32_e32 v77, 0xffff0000, v125
	v_and_b32_e32 v79, 0xffff0000, v124
	v_pk_fma_f32 v[20:21], v[20:21], v[78:79], v[72:73]
	v_pk_fma_f32 v[22:23], v[22:23], v[76:77], v[74:75]
	v_lshlrev_b32_e32 v72, 16, v96
	v_lshlrev_b32_e32 v74, 16, v97
	v_and_b32_e32 v73, 0xffff0000, v96
	v_and_b32_e32 v75, 0xffff0000, v97
	v_cndmask_b32_e32 v77, 0, v93, vcc
	v_cndmask_b32_e32 v76, 0, v92, vcc
	v_cndmask_b32_e32 v79, 0, v95, vcc
	v_cndmask_b32_e32 v78, 0, v94, vcc
	v_pk_fma_f32 v[22:23], v[78:79], v[74:75], v[22:23]
	v_pk_fma_f32 v[20:21], v[76:77], v[72:73], v[20:21]
	v_lshlrev_b32_e32 v72, 16, v81
	v_and_b32_e32 v73, 0xffff0000, v81
	v_lshlrev_b32_e32 v74, 16, v80
	v_and_b32_e32 v75, 0xffff0000, v80
	v_pk_fma_f32 v[22:23], v[106:107], v[72:73], v[22:23]
	v_pk_fma_f32 v[74:75], v[114:115], v[74:75], v[20:21]
	v_cvt_pk_bf16_f32 v21, v22, v23
	ds_write2_b32 v120, v22, v23 offset0:34 offset1:35
	ds_write2_b32 v120, v74, v75 offset0:32 offset1:33
	v_lshlrev_b32_e32 v22, 16, v132
	v_lshlrev_b32_e32 v72, 16, v133
	v_and_b32_e32 v23, 0xffff0000, v132
	v_and_b32_e32 v73, 0xffff0000, v133
	v_pk_fma_f32 v[42:43], v[70:71], v[72:73], v[42:43]
	v_pk_fma_f32 v[22:23], v[68:69], v[22:23], v[40:41]
	v_lshlrev_b32_e32 v40, 16, v127
	v_lshlrev_b32_e32 v68, 16, v126
	v_and_b32_e32 v41, 0xffff0000, v127
	v_and_b32_e32 v69, 0xffff0000, v126
	v_pk_fma_f32 v[22:23], v[36:37], v[68:69], v[22:23]
	v_pk_fma_f32 v[36:37], v[38:39], v[40:41], v[42:43]
	v_lshlrev_b32_e32 v38, 16, v98
	v_lshlrev_b32_e32 v40, 16, v99
	v_and_b32_e32 v39, 0xffff0000, v98
	v_and_b32_e32 v41, 0xffff0000, v99
	v_cndmask_b32_e32 v43, 0, v85, vcc
	v_cndmask_b32_e32 v42, 0, v84, vcc
	v_cndmask_b32_e32 v69, 0, v87, vcc
	v_cndmask_b32_e32 v68, 0, v86, vcc
	v_pk_fma_f32 v[36:37], v[68:69], v[40:41], v[36:37]
	v_pk_fma_f32 v[22:23], v[42:43], v[38:39], v[22:23]
	v_lshlrev_b32_e32 v38, 16, v83
	v_and_b32_e32 v39, 0xffff0000, v83
	v_lshlrev_b32_e32 v40, 16, v82
	v_and_b32_e32 v41, 0xffff0000, v82
	v_pk_fma_f32 v[36:37], v[116:117], v[38:39], v[36:37]
	v_pk_fma_f32 v[40:41], v[118:119], v[40:41], v[22:23]
	v_cvt_pk_bf16_f32 v23, v36, v37
	ds_write2_b32 v120, v36, v37 offset0:38 offset1:39
	ds_write2_b32 v120, v40, v41 offset0:36 offset1:37
	v_lshlrev_b32_e32 v36, 2, v122
	v_lshl_add_u64 v[118:119], s[92:93], 0, v[100:101]
	v_lshl_add_u64 v[120:121], s[34:35], 0, v[100:101]
	v_and_b32_e32 v143, 0xc0, v36
	v_lshl_add_u64 v[36:37], v[118:119], 0, v[2:3]
	v_lshl_add_u64 v[38:39], v[120:121], 0, v[2:3]
	s_nop 7
	s_waitcnt lgkmcnt(0)
	v_cvt_pk_bf16_f32 v20, v74, v75
	v_cvt_pk_bf16_f32 v22, v40, v41
	s_nop 7
	global_load_dwordx4 v[68:71], v[36:37], off offset:2048
	global_load_dwordx4 v[72:75], v[38:39], off offset:2048
	global_load_dwordx4 v[76:79], v[36:37], off offset:2112
	global_load_dwordx4 v[80:83], v[38:39], off offset:2112
	global_load_dwordx4 v[40:43], v[108:109], off offset:64
	s_nop 7
	global_load_dwordx4 v[36:39], v[110:111], off offset:64
	global_load_dwordx4 v[84:87], v[112:113], off offset:64
	s_nop 7
	v_mov_b32_e32 v104, 1.0
	s_nop 7
	v_mov_b32_e32 v105, 1.0
	s_nop 7
	v_cmp_eq_u32_e32 vcc, 0, v136
	s_nop 7
	v_mov_b32_e32 v145, v88
	s_nop 7
	v_mov_b32_e32 v147, v89
	s_nop 7
	v_mov_b32_e32 v103, 1.0
	s_nop 7
	v_mov_b32_e32 v2, v90
	s_nop 7
	v_mov_b32_e32 v100, 1.0
	s_nop 7
	v_mov_b32_e32 v101, 1.0
	s_nop 7
	v_mfma_f32_16x16x32_bf16 v[92:95], v[56:59], v[16:19], 0
	v_mov_b32_e32 v98, 1.0
	s_nop 7
	v_mfma_f32_16x16x32_bf16 v[92:95], v[64:67], v[32:35], v[92:95]
	v_mov_b32_e32 v99, 1.0
	s_nop 7
	v_mov_b32_e32 v146, v91
	v_and_b32_e32 v88, -16, v122
	v_add_u32_e32 v142, s6, v88
	v_lshlrev_b64 v[88:89], 1, v[0:1]
	v_lshl_add_u64 v[114:115], s[44:45], 0, v[88:89]
	v_lshl_add_u64 v[116:117], s[46:47], 0, v[88:89]
	v_and_b32_e32 v198, 16, v144
	v_lshrrev_b32_e32 v199, 1, v198
	v_add_u32_e32 v198, v198, v199
	v_mov_b32_e32 v199, 0
	v_lshl_add_u64 v[114:115], v[114:115], 0, v[198:199]
	v_lshl_add_u64 v[116:117], v[116:117], 0, v[198:199]
	v_mfma_f32_16x16x32_bf16 v[88:91], v[52:55], v[16:19], 0
	v_mad_u32_u24 v122, v136, s76, v142
	ds_read2_b32 v[124:125], v122 offset1:1
	ds_read2_b32 v[128:129], v122 offset0:2 offset1:3
	v_mfma_f32_16x16x32_bf16 v[88:91], v[60:63], v[32:35], v[88:91]
	v_mov_b32_e32 v102, 1.0
	v_add_u32_e32 v148, v142, v123
	v_add_u32_e32 v150, v142, v141
	s_nop 4
	v_add_f32_e32 v88, v48, v88
	v_add_f32_e32 v89, v49, v89
	v_mul_f32_e32 v88, 0xbfb8aa3b, v88
	v_mul_f32_e32 v89, 0xbfb8aa3b, v89
	v_exp_f32_e32 v88, v88
	v_exp_f32_e32 v89, v89
	v_add_f32_e32 v90, v50, v90
	v_mul_f32_e32 v90, 0xbfb8aa3b, v90
	v_add_f32_e32 v88, 1.0, v88
	v_add_f32_e32 v89, 1.0, v89
	v_rcp_f32_e32 v96, v88
	v_rcp_f32_e32 v97, v89
	v_add_f32_e32 v88, v44, v92
	v_add_f32_e32 v89, v45, v93
	v_mul_f32_e32 v92, 0xc1000000, v96
	v_mul_f32_e32 v93, 0xc1000000, v97
	v_mul_f32_e32 v88, 0xbfb8aa3b, v88
	v_mul_f32_e32 v92, v145, v92
	v_mul_f32_e32 v89, 0xbfb8aa3b, v89
	v_mul_f32_e32 v93, v147, v93
	v_exp_f32_e32 v88, v88
	v_mul_f32_e32 v92, 0x3fb8aa3b, v92
	v_exp_f32_e32 v89, v89
	v_mul_f32_e32 v93, 0x3fb8aa3b, v93
	v_exp_f32_e32 v92, v92
	v_exp_f32_e32 v93, v93
	v_add_f32_e32 v88, 1.0, v88
	v_add_f32_e32 v89, 1.0, v89
	v_rcp_f32_e32 v88, v88
	v_fma_f32 v96, -v92, v92, 1.0
	v_rcp_f32_e32 v89, v89
	v_fma_f32 v97, -v93, v93, 1.0
	v_sqrt_f32_e32 v96, v96
	v_sqrt_f32_e32 v97, v97
	s_waitcnt lgkmcnt(0)
; __device__ __forceinline__ unsigned pk2(float lo, float hi) { const f32x2_t v = {lo, hi}; const bf16x2_t b = __builtin_convertvector(v, bf16x2_t); return __builtin_bit_cast(unsigned, b); }
; __device__ __forceinline__ float sigmoidf_(float x) { return __builtin_amdgcn_rcpf(1.0f + __expf(-x)); }
; __device__ __forceinline__ float bcast15(float v, int lane) { return bperm_f((lane & 48) | 15, v); }
; __device__ __forceinline__ void w_lru_m1(const Args& a, int l, unsigned char* ws, const bf16_t* proj, bf16_t* y, LAS unsigned char* wl, int b, int ck_, int h, int lane) {
;     ...
;         for (int tb = 0; tb < 4; ++tb) { const int tok = 16 * tb + lo;
;             f32x4 ga = {0.f, 0.f, 0.f, 0.f}, gx = {0.f, 0.f, 0.f, 0.f};
; #pragma unroll
;             for (int kk = 0; kk < 2; ++kk) { ga = __builtin_amdgcn_mfma_f32_16x16x32_bf16(WaF[kk], Xf[tb][kk], ga, 0, 0, 0); gx = __builtin_amdgcn_mfma_f32_16x16x32_bf16(WxF[kk], Xf[tb][kk], gx, 0, 0, 0); }
;             float hv[4], pv[4];
; #pragma unroll
;             for (int r = 0; r < 4; ++r) {
;                 const float rg = sigmoidf_(ga[r] + bav[r]), ig = sigmoidf_(gx[r] + bxv[r]);
;                 const float la = -8.0f * rg * sp[r]; float A = __expf(la);
;                 float U = __builtin_amdgcn_sqrtf(1.0f - A * A) * (ig * xcf[tok * 65 + j0 + r]);
;                 { const float As = dpp_shr1<1>(A), Us = dpp_shr0<1>(U); U = A * Us + U; A = A * As; }
;                 { const float As = dpp_shr1<2>(A), Us = dpp_shr0<2>(U); U = A * Us + U; A = A * As; }
;                 { const float As = dpp_shr1<4>(A), Us = dpp_shr0<4>(U); U = A * Us + U; A = A * As; }
;                 { const float As = dpp_shr1<8>(A), Us = dpp_shr0<8>(U); U = A * Us + U; A = A * As; }
;                 const float hh = U + A * hc[r], PP = A * Pc[r];
;                 hc[r] = bcast15(hh, lane); Pc[r] = bcast15(PP, lane); hv[r] = hh; pv[r] = PP; }
;             *(unsigned long long*)(y + (size_t)(row0 + tok) * DM + 64 * h + j0) = (unsigned long long)pk2(hv[0], hv[1]) | ((unsigned long long)pk2(hv[2], hv[3]) << 32);
;             *(unsigned long long*)((bf16_t*)(ws + WS_P) + (size_t)(row0 + tok) * 512 + 64 * h + j0) = (unsigned long long)pk2(pv[0], pv[1]) | ((unsigned long long)pk2(pv[2], pv[3]) << 32);
;         }
	v_pk_mul_f32 v[88:89], v[124:125], v[88:89]
	v_mov_b32_dpp v98, v92 row_shr:1 row_mask:0xf bank_mask:0xf
	v_mov_b32_dpp v99, v93 row_shr:1 row_mask:0xf bank_mask:0xf
	v_pk_mul_f32 v[88:89], v[88:89], v[96:97]
	v_pk_mul_f32 v[98:99], v[92:93], v[98:99]
	v_exp_f32_e32 v90, v90
	v_mov_b32_dpp v96, v88 row_shr:1 row_mask:0xf bank_mask:0xf bound_ctrl:1
	v_mov_b32_dpp v97, v89 row_shr:1 row_mask:0xf bank_mask:0xf bound_ctrl:1
	v_pk_fma_f32 v[88:89], v[92:93], v[96:97], v[88:89]
	v_mov_b32_dpp v100, v98 row_shr:2 row_mask:0xf bank_mask:0xf
	v_mov_b32_dpp v101, v99 row_shr:2 row_mask:0xf bank_mask:0xf
	v_mov_b32_dpp v92, v88 row_shr:2 row_mask:0xf bank_mask:0xf bound_ctrl:1
	v_mov_b32_dpp v93, v89 row_shr:2 row_mask:0xf bank_mask:0xf bound_ctrl:1
	v_pk_fma_f32 v[88:89], v[98:99], v[92:93], v[88:89]
	v_pk_mul_f32 v[100:101], v[98:99], v[100:101]
	v_add_f32_e32 v90, 1.0, v90
	v_mov_b32_dpp v92, v88 row_shr:4 row_mask:0xf bank_mask:0xf bound_ctrl:1
	v_mov_b32_dpp v93, v89 row_shr:4 row_mask:0xf bank_mask:0xf bound_ctrl:1
	v_mov_b32_dpp v102, v100 row_shr:4 row_mask:0xf bank_mask:0xf
	v_mov_b32_dpp v103, v101 row_shr:4 row_mask:0xf bank_mask:0xf
	v_pk_fma_f32 v[88:89], v[100:101], v[92:93], v[88:89]
	v_pk_mul_f32 v[102:103], v[100:101], v[102:103]
	v_add_f32_e32 v91, v51, v91
	v_mov_b32_dpp v92, v88 row_shr:8 row_mask:0xf bank_mask:0xf bound_ctrl:1
	v_mov_b32_dpp v93, v89 row_shr:8 row_mask:0xf bank_mask:0xf bound_ctrl:1
	v_pk_fma_f32 v[88:89], v[102:103], v[92:93], v[88:89]
	v_rcp_f32_e32 v92, v90
	v_mul_f32_e32 v91, 0xbfb8aa3b, v91
	v_exp_f32_e32 v91, v91
	v_add_f32_e32 v90, v46, v94
	v_mul_f32_e32 v92, 0xc1000000, v92
	v_mul_f32_e32 v92, v2, v92
	v_mul_f32_e32 v92, 0x3fb8aa3b, v92
	v_exp_f32_e32 v92, v92
	v_add_f32_e32 v91, 1.0, v91
	v_mul_f32_e32 v90, 0xbfb8aa3b, v90
	v_exp_f32_e32 v90, v90
	v_fma_f32 v93, -v92, v92, 1.0
	v_sqrt_f32_e32 v94, v93
	v_rcp_f32_e32 v93, v91
	v_add_f32_e32 v91, v47, v95
	v_mul_f32_e32 v91, 0xbfb8aa3b, v91
	v_exp_f32_e32 v91, v91
	v_mul_f32_e32 v93, 0xc1000000, v93
	v_mul_f32_e32 v93, v146, v93
	v_mul_f32_e32 v93, 0x3fb8aa3b, v93
	v_exp_f32_e32 v93, v93
	v_add_f32_e32 v90, 1.0, v90
	v_add_f32_e32 v91, 1.0, v91
	v_rcp_f32_e32 v90, v90
	v_rcp_f32_e32 v91, v91
	v_fma_f32 v95, -v93, v93, 1.0
	v_sqrt_f32_e32 v95, v95
	v_mov_b32_e32 v96, 1.0
	v_pk_mul_f32 v[90:91], v[90:91], v[128:129]
	v_mov_b32_e32 v97, 1.0
	v_pk_mul_f32 v[90:91], v[94:95], v[90:91]
	v_mov_b32_dpp v96, v92 row_shr:1 row_mask:0xf bank_mask:0xf
	v_mov_b32_dpp v97, v93 row_shr:1 row_mask:0xf bank_mask:0xf
	v_mov_b32_dpp v94, v90 row_shr:1 row_mask:0xf bank_mask:0xf bound_ctrl:1
	v_mov_b32_dpp v95, v91 row_shr:1 row_mask:0xf bank_mask:0xf bound_ctrl:1
	v_pk_mul_f32 v[96:97], v[92:93], v[96:97]
	v_mov_b32_e32 v100, 1.0
	v_mov_b32_e32 v101, 1.0
	v_pk_fma_f32 v[90:91], v[92:93], v[94:95], v[90:91]
	v_mov_b32_dpp v104, v102 row_shr:8 row_mask:0xf bank_mask:0xf
	v_mov_b32_dpp v105, v103 row_shr:8 row_mask:0xf bank_mask:0xf
	v_mov_b32_dpp v100, v96 row_shr:2 row_mask:0xf bank_mask:0xf
	v_mov_b32_dpp v101, v97 row_shr:2 row_mask:0xf bank_mask:0xf
	v_mov_b32_dpp v92, v90 row_shr:2 row_mask:0xf bank_mask:0xf bound_ctrl:1
	v_mov_b32_dpp v93, v91 row_shr:2 row_mask:0xf bank_mask:0xf bound_ctrl:1
	v_pk_mul_f32 v[106:107], v[102:103], v[104:105]
	v_pk_mul_f32 v[100:101], v[96:97], v[100:101]
	v_mov_b32_e32 v102, 1.0
	v_mov_b32_e32 v103, 1.0
	v_pk_fma_f32 v[90:91], v[96:97], v[92:93], v[90:91]
	v_mov_b32_dpp v102, v100 row_shr:4 row_mask:0xf bank_mask:0xf
	v_mov_b32_dpp v103, v101 row_shr:4 row_mask:0xf bank_mask:0xf
	v_mov_b32_dpp v92, v90 row_shr:4 row_mask:0xf bank_mask:0xf bound_ctrl:1
	v_mov_b32_dpp v93, v91 row_shr:4 row_mask:0xf bank_mask:0xf bound_ctrl:1
	v_pk_mul_f32 v[102:103], v[100:101], v[102:103]
	v_mov_b32_e32 v124, 1.0
	v_mov_b32_e32 v125, 1.0
	v_pk_fma_f32 v[90:91], v[100:101], v[92:93], v[90:91]
	v_mov_b32_dpp v124, v102 row_shr:8 row_mask:0xf bank_mask:0xf
	v_mov_b32_dpp v125, v103 row_shr:8 row_mask:0xf bank_mask:0xf
	v_mov_b32_dpp v92, v90 row_shr:8 row_mask:0xf bank_mask:0xf bound_ctrl:1
	v_mov_b32_dpp v93, v91 row_shr:8 row_mask:0xf bank_mask:0xf bound_ctrl:1
	v_pk_mul_f32 v[126:127], v[102:103], v[124:125]
	v_pk_fma_f32 v[90:91], v[102:103], v[92:93], v[90:91]
	v_pk_fma_f32 v[88:89], v[106:107], 0, v[88:89] op_sel_hi:[1,0,1]
	v_pk_fma_f32 v[90:91], v[126:127], 0, v[90:91] op_sel_hi:[1,0,1]
	ds_bpermute_b32 v98, v143, v88 offset:60
	ds_bpermute_b32 v99, v143, v89 offset:60
	ds_bpermute_b32 v96, v143, v90 offset:60
	v_cvt_pk_bf16_f32 v88, v88, v89
	v_cvt_pk_bf16_f32 v89, v90, v91
	v_or_b32_e32 v90, s48, v136
	ds_bpermute_b32 v97, v143, v91 offset:60
	v_ashrrev_i32_e32 v91, 31, v90
	v_lshlrev_b64 v[92:93], 11, v[90:91]
	v_lshl_add_u64 v[100:101], v[114:115], 0, v[92:93]
	v_lshlrev_b64 v[90:91], 10, v[90:91]
	v_mov_b64_e32 v[222:223], v[88:89]
	v_cvt_pk_bf16_f32 v88, v106, v107
	v_cvt_pk_bf16_f32 v89, v126, v127
	v_lshl_add_u64 v[102:103], v[116:117], 0, v[90:91]
	v_mov_b64_e32 v[226:227], v[88:89]
	v_mfma_f32_16x16x32_bf16 v[88:91], v[52:55], v[12:15], 0
	ds_bpermute_b32 v124, v143, v126 offset:60
	ds_bpermute_b32 v125, v143, v127 offset:60
	ds_bpermute_b32 v104, v143, v106 offset:60
	v_mfma_f32_16x16x32_bf16 v[126:129], v[56:59], v[12:15], 0
	ds_bpermute_b32 v105, v143, v107 offset:60
	v_mfma_f32_16x16x32_bf16 v[92:95], v[60:63], v[28:31], v[88:91]
	v_mfma_f32_16x16x32_bf16 v[88:91], v[64:67], v[28:31], v[126:129]
	s_nop 6
	v_add_f32_e32 v92, v48, v92
	v_mul_f32_e32 v92, 0xbfb8aa3b, v92
	v_exp_f32_e32 v92, v92
	v_add_f32_e32 v88, v44, v88
	v_mul_f32_e32 v88, 0xbfb8aa3b, v88
	v_exp_f32_e32 v88, v88
	v_add_f32_e32 v92, 1.0, v92
	v_rcp_f32_e32 v92, v92
; __device__ __forceinline__ unsigned pk2(float lo, float hi) { const f32x2_t v = {lo, hi}; const bf16x2_t b = __builtin_convertvector(v, bf16x2_t); return __builtin_bit_cast(unsigned, b); }
; __device__ __forceinline__ float sigmoidf_(float x) { return __builtin_amdgcn_rcpf(1.0f + __expf(-x)); }
; __device__ __forceinline__ float bcast15(float v, int lane) { return bperm_f((lane & 48) | 15, v); }
; __device__ __forceinline__ void w_lru_m1(const Args& a, int l, unsigned char* ws, const bf16_t* proj, bf16_t* y, LAS unsigned char* wl, int b, int ck_, int h, int lane) {
;     ...
;         for (int tb = 0; tb < 4; ++tb) { const int tok = 16 * tb + lo;
;             f32x4 ga = {0.f, 0.f, 0.f, 0.f}, gx = {0.f, 0.f, 0.f, 0.f};
; #pragma unroll
;             for (int kk = 0; kk < 2; ++kk) { ga = __builtin_amdgcn_mfma_f32_16x16x32_bf16(WaF[kk], Xf[tb][kk], ga, 0, 0, 0); gx = __builtin_amdgcn_mfma_f32_16x16x32_bf16(WxF[kk], Xf[tb][kk], gx, 0, 0, 0); }
;             float hv[4], pv[4];
; #pragma unroll
;             for (int r = 0; r < 4; ++r) {
;                 const float rg = sigmoidf_(ga[r] + bav[r]), ig = sigmoidf_(gx[r] + bxv[r]);
;                 const float la = -8.0f * rg * sp[r]; float A = __expf(la);
;                 float U = __builtin_amdgcn_sqrtf(1.0f - A * A) * (ig * xcf[tok * 65 + j0 + r]);
;                 { const float As = dpp_shr1<1>(A), Us = dpp_shr0<1>(U); U = A * Us + U; A = A * As; }
;                 { const float As = dpp_shr1<2>(A), Us = dpp_shr0<2>(U); U = A * Us + U; A = A * As; }
;                 { const float As = dpp_shr1<4>(A), Us = dpp_shr0<4>(U); U = A * Us + U; A = A * As; }
;                 { const float As = dpp_shr1<8>(A), Us = dpp_shr0<8>(U); U = A * Us + U; A = A * As; }
;                 const float hh = U + A * hc[r], PP = A * Pc[r];
;                 hc[r] = bcast15(hh, lane); Pc[r] = bcast15(PP, lane); hv[r] = hh; pv[r] = PP; }
;             *(unsigned long long*)(y + (size_t)(row0 + tok) * DM + 64 * h + j0) = (unsigned long long)pk2(hv[0], hv[1]) | ((unsigned long long)pk2(hv[2], hv[3]) << 32);
;             *(unsigned long long*)((bf16_t*)(ws + WS_P) + (size_t)(row0 + tok) * 512 + 64 * h + j0) = (unsigned long long)pk2(pv[0], pv[1]) | ((unsigned long long)pk2(pv[2], pv[3]) << 32);
;         }
	v_add_f32_e32 v89, v45, v89
	v_add_f32_e32 v88, 1.0, v88
	v_rcp_f32_e32 v106, v88
	v_mul_f32_e32 v88, 0xc1000000, v92
	v_add_f32_e32 v92, v49, v93
	v_mul_f32_e32 v92, 0xbfb8aa3b, v92
	v_exp_f32_e32 v92, v92
	v_mul_f32_e32 v89, 0xbfb8aa3b, v89
	v_exp_f32_e32 v89, v89
	v_mul_f32_e32 v88, v145, v88
	v_add_f32_e32 v92, 1.0, v92
	v_rcp_f32_e32 v92, v92
	v_add_f32_e32 v89, 1.0, v89
	v_rcp_f32_e32 v107, v89
	v_mul_f32_e32 v88, 0x3fb8aa3b, v88
	v_mul_f32_e32 v89, 0xc1000000, v92
	v_mul_f32_e32 v89, v147, v89
	v_mul_f32_e32 v89, 0x3fb8aa3b, v89
	v_exp_f32_e32 v122, v88
	v_exp_f32_e32 v123, v89
	v_add_f32_e32 v94, v50, v94
	v_add_f32_e32 v95, v51, v95
	v_fma_f32 v88, -v122, v122, 1.0
	v_fma_f32 v89, -v123, v123, 1.0
	v_sqrt_f32_e32 v126, v88
	v_mov_b32_e32 v88, 1.0
	v_sqrt_f32_e32 v127, v89
	v_mov_b32_e32 v89, 1.0
	v_mov_b32_dpp v88, v122 row_shr:1 row_mask:0xf bank_mask:0xf
	v_mul_f32_e32 v94, 0xbfb8aa3b, v94
	v_mov_b32_dpp v89, v123 row_shr:1 row_mask:0xf bank_mask:0xf
	v_pk_mul_f32 v[128:129], v[122:123], v[88:89]
	v_mov_b32_e32 v88, 1.0
	v_mov_b32_e32 v89, 1.0
	v_mul_f32_e32 v95, 0xbfb8aa3b, v95
	v_mov_b32_dpp v88, v128 row_shr:2 row_mask:0xf bank_mask:0xf
	v_mov_b32_dpp v89, v129 row_shr:2 row_mask:0xf bank_mask:0xf
	v_pk_mul_f32 v[130:131], v[128:129], v[88:89]
	v_mov_b32_e32 v88, 1.0
	v_mov_b32_e32 v89, 1.0
	v_exp_f32_e32 v94, v94
	v_mov_b32_dpp v88, v130 row_shr:4 row_mask:0xf bank_mask:0xf
	v_mov_b32_dpp v89, v131 row_shr:4 row_mask:0xf bank_mask:0xf
	v_pk_mul_f32 v[132:133], v[130:131], v[88:89]
	v_mov_b32_e32 v88, 1.0
	v_mov_b32_e32 v89, 1.0
	v_exp_f32_e32 v95, v95
	v_mov_b32_dpp v88, v132 row_shr:8 row_mask:0xf bank_mask:0xf
	v_mov_b32_dpp v89, v133 row_shr:8 row_mask:0xf bank_mask:0xf
	v_pk_mul_f32 v[134:135], v[132:133], v[88:89]
	v_add_f32_e32 v90, v46, v90
	s_waitcnt lgkmcnt(0)
	v_pk_mul_f32 v[92:93], v[134:135], v[104:105]
	ds_read2_b32 v[104:105], v148 offset1:1
	v_add_f32_e32 v91, v47, v91
	v_mul_f32_e32 v90, 0xbfb8aa3b, v90
	v_mul_f32_e32 v91, 0xbfb8aa3b, v91
	v_add_f32_e32 v94, 1.0, v94
	s_waitcnt lgkmcnt(0)
	v_pk_mul_f32 v[104:105], v[104:105], v[106:107]
	v_exp_f32_e32 v90, v90
	v_pk_mul_f32 v[104:105], v[104:105], v[126:127]
	v_add_f32_e32 v95, 1.0, v95
	v_exp_f32_e32 v91, v91
	v_mov_b32_dpp v106, v104 row_shr:1 row_mask:0xf bank_mask:0xf bound_ctrl:1
	v_mov_b32_dpp v107, v105 row_shr:1 row_mask:0xf bank_mask:0xf bound_ctrl:1
	v_pk_fma_f32 v[104:105], v[122:123], v[106:107], v[104:105]
	v_rcp_f32_e32 v94, v94
	v_rcp_f32_e32 v95, v95
	v_mov_b32_dpp v106, v104 row_shr:2 row_mask:0xf bank_mask:0xf bound_ctrl:1
	v_mov_b32_dpp v107, v105 row_shr:2 row_mask:0xf bank_mask:0xf bound_ctrl:1
	v_pk_fma_f32 v[104:105], v[128:129], v[106:107], v[104:105]
	v_add_f32_e32 v90, 1.0, v90
	v_add_f32_e32 v91, 1.0, v91
	v_mov_b32_dpp v106, v104 row_shr:4 row_mask:0xf bank_mask:0xf bound_ctrl:1
	v_mov_b32_dpp v107, v105 row_shr:4 row_mask:0xf bank_mask:0xf bound_ctrl:1
	v_pk_fma_f32 v[104:105], v[130:131], v[106:107], v[104:105]
	ds_bpermute_b32 v88, v143, v92 offset:60
	ds_bpermute_b32 v89, v143, v93 offset:60
	v_mov_b32_dpp v106, v104 row_shr:8 row_mask:0xf bank_mask:0xf bound_ctrl:1
	v_mov_b32_dpp v107, v105 row_shr:8 row_mask:0xf bank_mask:0xf bound_ctrl:1
	v_pk_fma_f32 v[104:105], v[132:133], v[106:107], v[104:105]
	v_rcp_f32_e32 v106, v90
	v_mul_f32_e32 v90, 0xc1000000, v94
	v_rcp_f32_e32 v107, v91
	v_mul_f32_e32 v91, 0xc1000000, v95
	v_mul_f32_e32 v90, v2, v90
	v_mul_f32_e32 v91, v146, v91
	v_mul_f32_e32 v90, 0x3fb8aa3b, v90
	v_mul_f32_e32 v91, 0x3fb8aa3b, v91
	v_exp_f32_e32 v94, v90
	v_exp_f32_e32 v95, v91
	v_pk_fma_f32 v[104:105], v[134:135], v[98:99], v[104:105]
	ds_read2_b32 v[134:135], v148 offset0:2 offset1:3
	v_fma_f32 v90, -v94, v94, 1.0
	v_fma_f32 v91, -v95, v95, 1.0
	v_sqrt_f32_e32 v122, v90
	v_sqrt_f32_e32 v123, v91
	s_waitcnt lgkmcnt(0)
	v_pk_mul_f32 v[106:107], v[106:107], v[134:135]
	v_mov_b32_e32 v90, 1.0
	v_mov_b32_e32 v91, 1.0
	v_pk_mul_f32 v[106:107], v[122:123], v[106:107]
	v_mov_b32_dpp v90, v94 row_shr:1 row_mask:0xf bank_mask:0xf
	v_mov_b32_dpp v91, v95 row_shr:1 row_mask:0xf bank_mask:0xf
	v_mov_b32_dpp v122, v106 row_shr:1 row_mask:0xf bank_mask:0xf bound_ctrl:1
	v_mov_b32_dpp v123, v107 row_shr:1 row_mask:0xf bank_mask:0xf bound_ctrl:1
	v_pk_mul_f32 v[126:127], v[94:95], v[90:91]
	v_mov_b32_e32 v90, 1.0
	v_mov_b32_e32 v91, 1.0
	v_pk_fma_f32 v[94:95], v[94:95], v[122:123], v[106:107]
	v_mov_b32_dpp v90, v126 row_shr:2 row_mask:0xf bank_mask:0xf
	v_mov_b32_dpp v91, v127 row_shr:2 row_mask:0xf bank_mask:0xf
	v_mov_b32_dpp v106, v94 row_shr:2 row_mask:0xf bank_mask:0xf bound_ctrl:1
	v_mov_b32_dpp v107, v95 row_shr:2 row_mask:0xf bank_mask:0xf bound_ctrl:1
	v_pk_mul_f32 v[128:129], v[126:127], v[90:91]
	v_mov_b32_e32 v90, 1.0
	v_mov_b32_e32 v91, 1.0
	v_pk_fma_f32 v[94:95], v[126:127], v[106:107], v[94:95]
	v_mov_b32_dpp v90, v128 row_shr:4 row_mask:0xf bank_mask:0xf
	v_mov_b32_dpp v91, v129 row_shr:4 row_mask:0xf bank_mask:0xf
	v_mov_b32_dpp v106, v94 row_shr:4 row_mask:0xf bank_mask:0xf bound_ctrl:1
	v_mov_b32_dpp v107, v95 row_shr:4 row_mask:0xf bank_mask:0xf bound_ctrl:1
	v_pk_mul_f32 v[130:131], v[128:129], v[90:91]
	v_mov_b32_e32 v90, 1.0
	v_mov_b32_e32 v91, 1.0
	v_pk_fma_f32 v[94:95], v[128:129], v[106:107], v[94:95]
	v_mov_b32_dpp v90, v130 row_shr:8 row_mask:0xf bank_mask:0xf
	v_mov_b32_dpp v91, v131 row_shr:8 row_mask:0xf bank_mask:0xf
	v_mov_b32_dpp v106, v94 row_shr:8 row_mask:0xf bank_mask:0xf bound_ctrl:1
	v_mov_b32_dpp v107, v95 row_shr:8 row_mask:0xf bank_mask:0xf bound_ctrl:1
	v_pk_mul_f32 v[132:133], v[130:131], v[90:91]
	v_pk_fma_f32 v[94:95], v[130:131], v[106:107], v[94:95]
; __device__ __forceinline__ unsigned pk2(float lo, float hi) { const f32x2_t v = {lo, hi}; const bf16x2_t b = __builtin_convertvector(v, bf16x2_t); return __builtin_bit_cast(unsigned, b); }
; __device__ __forceinline__ float sigmoidf_(float x) { return __builtin_amdgcn_rcpf(1.0f + __expf(-x)); }
; __device__ __forceinline__ float bcast15(float v, int lane) { return bperm_f((lane & 48) | 15, v); }
; __device__ __forceinline__ void w_lru_m1(const Args& a, int l, unsigned char* ws, const bf16_t* proj, bf16_t* y, LAS unsigned char* wl, int b, int ck_, int h, int lane) {
;     ...
;         for (int tb = 0; tb < 4; ++tb) { const int tok = 16 * tb + lo;
;             f32x4 ga = {0.f, 0.f, 0.f, 0.f}, gx = {0.f, 0.f, 0.f, 0.f};
; #pragma unroll
;             for (int kk = 0; kk < 2; ++kk) { ga = __builtin_amdgcn_mfma_f32_16x16x32_bf16(WaF[kk], Xf[tb][kk], ga, 0, 0, 0); gx = __builtin_amdgcn_mfma_f32_16x16x32_bf16(WxF[kk], Xf[tb][kk], gx, 0, 0, 0); }
;             float hv[4], pv[4];
; #pragma unroll
;             for (int r = 0; r < 4; ++r) {
;                 const float rg = sigmoidf_(ga[r] + bav[r]), ig = sigmoidf_(gx[r] + bxv[r]);
;                 const float la = -8.0f * rg * sp[r]; float A = __expf(la);
;                 float U = __builtin_amdgcn_sqrtf(1.0f - A * A) * (ig * xcf[tok * 65 + j0 + r]);
;                 { const float As = dpp_shr1<1>(A), Us = dpp_shr0<1>(U); U = A * Us + U; A = A * As; }
;                 { const float As = dpp_shr1<2>(A), Us = dpp_shr0<2>(U); U = A * Us + U; A = A * As; }
;                 { const float As = dpp_shr1<4>(A), Us = dpp_shr0<4>(U); U = A * Us + U; A = A * As; }
;                 { const float As = dpp_shr1<8>(A), Us = dpp_shr0<8>(U); U = A * Us + U; A = A * As; }
;                 const float hh = U + A * hc[r], PP = A * Pc[r];
;                 hc[r] = bcast15(hh, lane); Pc[r] = bcast15(PP, lane); hv[r] = hh; pv[r] = PP; }
;             *(unsigned long long*)(y + (size_t)(row0 + tok) * DM + 64 * h + j0) = (unsigned long long)pk2(hv[0], hv[1]) | ((unsigned long long)pk2(hv[2], hv[3]) << 32);
;             *(unsigned long long*)((bf16_t*)(ws + WS_P) + (size_t)(row0 + tok) * 512 + 64 * h + j0) = (unsigned long long)pk2(pv[0], pv[1]) | ((unsigned long long)pk2(pv[2], pv[3]) << 32);
;         }
	ds_bpermute_b32 v98, v143, v104 offset:60
	v_pk_fma_f32 v[94:95], v[132:133], v[96:97], v[94:95]
	ds_bpermute_b32 v96, v143, v94 offset:60
	v_cvt_pk_bf16_f32 v107, v94, v95
	v_or_b32_e32 v94, s48, v140
	ds_bpermute_b32 v97, v143, v95 offset:60
	v_ashrrev_i32_e32 v95, 31, v94
	ds_bpermute_b32 v99, v143, v105 offset:60
	v_cvt_pk_bf16_f32 v106, v104, v105
	v_lshlrev_b64 v[104:105], 11, v[94:95]
	v_pk_mul_f32 v[124:125], v[132:133], v[124:125]
	v_lshl_add_u64 v[104:105], v[114:115], 0, v[104:105]
	v_lshlrev_b64 v[94:95], 10, v[94:95]
	v_mov_b64_e32 v[230:231], v[106:107]
	v_cvt_pk_bf16_f32 v92, v92, v93
	v_cvt_pk_bf16_f32 v93, v124, v125
	v_lshl_add_u64 v[106:107], v[116:117], 0, v[94:95]
	v_mov_b64_e32 v[234:235], v[92:93]
	v_mfma_f32_16x16x32_bf16 v[92:95], v[52:55], v[8:11], 0
	ds_bpermute_b32 v90, v143, v124 offset:60
	ds_bpermute_b32 v91, v143, v125 offset:60
	v_mfma_f32_16x16x32_bf16 v[126:129], v[60:63], v[24:27], v[92:95]
	v_mfma_f32_16x16x32_bf16 v[122:125], v[56:59], v[8:11], 0
	v_mfma_f32_16x16x32_bf16 v[122:125], v[64:67], v[24:27], v[122:125]
	s_nop 5
	v_add_f32_e32 v92, v48, v126
	v_mul_f32_e32 v92, 0xbfb8aa3b, v92
	v_exp_f32_e32 v92, v92
	v_mfma_f32_16x16x32_bf16 v[52:55], v[52:55], v[4:7], 0
	v_add_f32_e32 v92, 1.0, v92
	v_rcp_f32_e32 v93, v92
	v_add_f32_e32 v92, v44, v122
	v_mov_b32_e32 v122, 1.0
	v_mul_f32_e32 v92, 0xbfb8aa3b, v92
	v_mul_f32_e32 v93, 0xc1000000, v93
	v_mul_f32_e32 v93, v145, v93
	v_mul_f32_e32 v93, 0x3fb8aa3b, v93
	v_exp_f32_e32 v94, v93
	v_exp_f32_e32 v92, v92
	v_fma_f32 v93, -v94, v94, 1.0
	v_sqrt_f32_e32 v126, v93
	v_add_f32_e32 v93, v49, v127
	v_mul_f32_e32 v93, 0xbfb8aa3b, v93
	v_exp_f32_e32 v93, v93
	v_mov_b32_dpp v122, v94 row_shr:1 row_mask:0xf bank_mask:0xf
	v_add_f32_e32 v92, 1.0, v92
	v_rcp_f32_e32 v92, v92
	v_add_f32_e32 v93, 1.0, v93
	v_rcp_f32_e32 v95, v93
	v_add_f32_e32 v93, v45, v123
	v_mul_f32_e32 v93, 0xbfb8aa3b, v93
	v_exp_f32_e32 v93, v93
	v_mul_f32_e32 v95, 0xc1000000, v95
	v_mul_f32_e32 v95, v147, v95
	v_mul_f32_e32 v95, 0x3fb8aa3b, v95
	v_exp_f32_e32 v95, v95
	v_add_f32_e32 v93, 1.0, v93
	v_rcp_f32_e32 v93, v93
	v_fma_f32 v123, -v95, v95, 1.0
	v_sqrt_f32_e32 v127, v123
	v_mov_b32_e32 v123, 1.0
	s_nop 1
	v_mov_b32_dpp v123, v95 row_shr:1 row_mask:0xf bank_mask:0xf
	v_pk_mul_f32 v[130:131], v[94:95], v[122:123]
	v_mov_b32_e32 v122, 1.0
	v_mov_b32_e32 v123, 1.0
	s_nop 0
	v_mov_b32_dpp v122, v130 row_shr:2 row_mask:0xf bank_mask:0xf
	v_mov_b32_dpp v123, v131 row_shr:2 row_mask:0xf bank_mask:0xf
	v_pk_mul_f32 v[132:133], v[130:131], v[122:123]
	v_mov_b32_e32 v122, 1.0
	v_mov_b32_e32 v123, 1.0
	s_nop 0
	v_mov_b32_dpp v122, v132 row_shr:4 row_mask:0xf bank_mask:0xf
	v_mov_b32_dpp v123, v133 row_shr:4 row_mask:0xf bank_mask:0xf
	v_pk_mul_f32 v[134:135], v[132:133], v[122:123]
	v_mov_b32_e32 v122, 1.0
	v_mov_b32_e32 v123, 1.0
	s_nop 0
	v_mov_b32_dpp v122, v134 row_shr:8 row_mask:0xf bank_mask:0xf
	v_mov_b32_dpp v123, v135 row_shr:8 row_mask:0xf bank_mask:0xf
	v_pk_mul_f32 v[140:141], v[134:135], v[122:123]
	s_nop 0
	v_pk_mul_f32 v[148:149], v[140:141], v[88:89]
	ds_read2_b32 v[88:89], v150 offset1:1
	ds_bpermute_b32 v122, v143, v148 offset:60
	ds_bpermute_b32 v123, v143, v149 offset:60
	s_waitcnt lgkmcnt(0)
	v_pk_mul_f32 v[88:89], v[88:89], v[92:93]
	s_nop 0
	v_pk_mul_f32 v[88:89], v[88:89], v[126:127]
	s_nop 1
	v_mov_b32_dpp v92, v88 row_shr:1 row_mask:0xf bank_mask:0xf bound_ctrl:1
	v_mov_b32_dpp v93, v89 row_shr:1 row_mask:0xf bank_mask:0xf bound_ctrl:1
	v_pk_fma_f32 v[88:89], v[94:95], v[92:93], v[88:89]
	s_nop 1
	v_mov_b32_dpp v92, v88 row_shr:2 row_mask:0xf bank_mask:0xf bound_ctrl:1
	v_mov_b32_dpp v93, v89 row_shr:2 row_mask:0xf bank_mask:0xf bound_ctrl:1
	v_pk_fma_f32 v[88:89], v[130:131], v[92:93], v[88:89]
	s_nop 1
	v_mov_b32_dpp v92, v88 row_shr:4 row_mask:0xf bank_mask:0xf bound_ctrl:1
	v_mov_b32_dpp v93, v89 row_shr:4 row_mask:0xf bank_mask:0xf bound_ctrl:1
	v_pk_fma_f32 v[88:89], v[132:133], v[92:93], v[88:89]
	s_nop 1
	v_mov_b32_dpp v92, v88 row_shr:8 row_mask:0xf bank_mask:0xf bound_ctrl:1
	v_mov_b32_dpp v93, v89 row_shr:8 row_mask:0xf bank_mask:0xf bound_ctrl:1
	v_pk_fma_f32 v[88:89], v[134:135], v[92:93], v[88:89]
	v_mov_b32_e32 v92, 1.0
	v_pk_fma_f32 v[98:99], v[140:141], v[98:99], v[88:89]
	v_add_f32_e32 v88, v50, v128
	v_mul_f32_e32 v88, 0xbfb8aa3b, v88
	v_exp_f32_e32 v88, v88
	ds_read2_b32 v[140:141], v150 offset0:2 offset1:3
	ds_bpermute_b32 v94, v143, v98 offset:60
	ds_bpermute_b32 v95, v143, v99 offset:60
	v_add_f32_e32 v88, 1.0, v88
	v_rcp_f32_e32 v89, v88
	v_add_f32_e32 v88, v46, v124
	v_mul_f32_e32 v88, 0xbfb8aa3b, v88
	v_exp_f32_e32 v88, v88
	v_mul_f32_e32 v89, 0xc1000000, v89
	v_mul_f32_e32 v89, v2, v89
	v_mul_f32_e32 v89, 0x3fb8aa3b, v89
	v_exp_f32_e32 v124, v89
	v_add_f32_e32 v88, 1.0, v88
	v_rcp_f32_e32 v88, v88
	v_cvt_pk_bf16_f32 v98, v98, v99
	v_fma_f32 v89, -v124, v124, 1.0
	v_sqrt_f32_e32 v126, v89
	v_add_f32_e32 v89, v51, v129
	v_mul_f32_e32 v89, 0xbfb8aa3b, v89
	v_exp_f32_e32 v89, v89
	v_mov_b32_dpp v92, v124 row_shr:1 row_mask:0xf bank_mask:0xf
	v_add_f32_e32 v89, 1.0, v89
	v_rcp_f32_e32 v93, v89
	v_add_f32_e32 v89, v47, v125
	v_mul_f32_e32 v89, 0xbfb8aa3b, v89
	v_exp_f32_e32 v89, v89
	v_mul_f32_e32 v93, 0xc1000000, v93
	v_mul_f32_e32 v93, v146, v93
	v_mul_f32_e32 v93, 0x3fb8aa3b, v93
	v_exp_f32_e32 v125, v93
	v_add_f32_e32 v89, 1.0, v89
	v_rcp_f32_e32 v89, v89
	v_fma_f32 v93, -v125, v125, 1.0
	v_sqrt_f32_e32 v127, v93
	s_waitcnt lgkmcnt(0)
; __device__ __forceinline__ unsigned pk2(float lo, float hi) { const f32x2_t v = {lo, hi}; const bf16x2_t b = __builtin_convertvector(v, bf16x2_t); return __builtin_bit_cast(unsigned, b); }
; __device__ __forceinline__ float sigmoidf_(float x) { return __builtin_amdgcn_rcpf(1.0f + __expf(-x)); }
; __device__ __forceinline__ float bcast15(float v, int lane) { return bperm_f((lane & 48) | 15, v); }
; __device__ __forceinline__ void w_lru_m1(const Args& a, int l, unsigned char* ws, const bf16_t* proj, bf16_t* y, LAS unsigned char* wl, int b, int ck_, int h, int lane) {
;     ...
;         for (int tb = 0; tb < 4; ++tb) { const int tok = 16 * tb + lo;
;             f32x4 ga = {0.f, 0.f, 0.f, 0.f}, gx = {0.f, 0.f, 0.f, 0.f};
; #pragma unroll
;             for (int kk = 0; kk < 2; ++kk) { ga = __builtin_amdgcn_mfma_f32_16x16x32_bf16(WaF[kk], Xf[tb][kk], ga, 0, 0, 0); gx = __builtin_amdgcn_mfma_f32_16x16x32_bf16(WxF[kk], Xf[tb][kk], gx, 0, 0, 0); }
;             float hv[4], pv[4];
; #pragma unroll
;             for (int r = 0; r < 4; ++r) {
;                 const float rg = sigmoidf_(ga[r] + bav[r]), ig = sigmoidf_(gx[r] + bxv[r]);
;                 const float la = -8.0f * rg * sp[r]; float A = __expf(la);
;                 float U = __builtin_amdgcn_sqrtf(1.0f - A * A) * (ig * xcf[tok * 65 + j0 + r]);
;                 { const float As = dpp_shr1<1>(A), Us = dpp_shr0<1>(U); U = A * Us + U; A = A * As; }
;                 { const float As = dpp_shr1<2>(A), Us = dpp_shr0<2>(U); U = A * Us + U; A = A * As; }
;                 { const float As = dpp_shr1<4>(A), Us = dpp_shr0<4>(U); U = A * Us + U; A = A * As; }
;                 { const float As = dpp_shr1<8>(A), Us = dpp_shr0<8>(U); U = A * Us + U; A = A * As; }
;                 const float hh = U + A * hc[r], PP = A * Pc[r];
;                 hc[r] = bcast15(hh, lane); Pc[r] = bcast15(PP, lane); hv[r] = hh; pv[r] = PP; }
;             *(unsigned long long*)(y + (size_t)(row0 + tok) * DM + 64 * h + j0) = (unsigned long long)pk2(hv[0], hv[1]) | ((unsigned long long)pk2(hv[2], hv[3]) << 32);
;             *(unsigned long long*)((bf16_t*)(ws + WS_P) + (size_t)(row0 + tok) * 512 + 64 * h + j0) = (unsigned long long)pk2(pv[0], pv[1]) | ((unsigned long long)pk2(pv[2], pv[3]) << 32);
;         }
	v_pk_mul_f32 v[88:89], v[88:89], v[140:141]
	v_mov_b32_e32 v93, 1.0
	v_pk_mul_f32 v[88:89], v[126:127], v[88:89]
	s_nop 0
	v_mov_b32_dpp v93, v125 row_shr:1 row_mask:0xf bank_mask:0xf
	v_mov_b32_dpp v126, v88 row_shr:1 row_mask:0xf bank_mask:0xf bound_ctrl:1
	v_mov_b32_dpp v127, v89 row_shr:1 row_mask:0xf bank_mask:0xf bound_ctrl:1
	v_pk_mul_f32 v[128:129], v[124:125], v[92:93]
	v_mov_b32_e32 v92, 1.0
	v_mov_b32_e32 v93, 1.0
	v_pk_fma_f32 v[88:89], v[124:125], v[126:127], v[88:89]
	v_mov_b32_dpp v92, v128 row_shr:2 row_mask:0xf bank_mask:0xf
	v_mov_b32_dpp v93, v129 row_shr:2 row_mask:0xf bank_mask:0xf
	v_mov_b32_dpp v124, v88 row_shr:2 row_mask:0xf bank_mask:0xf bound_ctrl:1
	v_mov_b32_dpp v125, v89 row_shr:2 row_mask:0xf bank_mask:0xf bound_ctrl:1
	v_pk_mul_f32 v[130:131], v[128:129], v[92:93]
	v_mov_b32_e32 v92, 1.0
	v_mov_b32_e32 v93, 1.0
	v_pk_fma_f32 v[88:89], v[128:129], v[124:125], v[88:89]
	v_mov_b32_dpp v92, v130 row_shr:4 row_mask:0xf bank_mask:0xf
	v_mov_b32_dpp v93, v131 row_shr:4 row_mask:0xf bank_mask:0xf
	v_mov_b32_dpp v124, v88 row_shr:4 row_mask:0xf bank_mask:0xf bound_ctrl:1
	v_mov_b32_dpp v125, v89 row_shr:4 row_mask:0xf bank_mask:0xf bound_ctrl:1
	v_pk_mul_f32 v[132:133], v[130:131], v[92:93]
	v_mov_b32_e32 v92, 1.0
	v_mov_b32_e32 v93, 1.0
	v_pk_fma_f32 v[88:89], v[130:131], v[124:125], v[88:89]
	v_mov_b32_dpp v92, v132 row_shr:8 row_mask:0xf bank_mask:0xf
	v_mov_b32_dpp v93, v133 row_shr:8 row_mask:0xf bank_mask:0xf
	v_mov_b32_dpp v124, v88 row_shr:8 row_mask:0xf bank_mask:0xf bound_ctrl:1
	v_mov_b32_dpp v125, v89 row_shr:8 row_mask:0xf bank_mask:0xf bound_ctrl:1
	v_pk_mul_f32 v[134:135], v[132:133], v[92:93]
	v_pk_fma_f32 v[88:89], v[132:133], v[124:125], v[88:89]
	v_or_b32_e32 v124, s48, v139
	v_pk_fma_f32 v[96:97], v[134:135], v[96:97], v[88:89]
	v_ashrrev_i32_e32 v125, 31, v124
	v_pk_mul_f32 v[90:91], v[134:135], v[90:91]
	ds_bpermute_b32 v88, v143, v96 offset:60
	ds_bpermute_b32 v89, v143, v97 offset:60
	v_cvt_pk_bf16_f32 v99, v96, v97
	v_lshlrev_b64 v[96:97], 11, v[124:125]
	ds_bpermute_b32 v92, v143, v90 offset:60
	ds_bpermute_b32 v93, v143, v91 offset:60
	v_lshl_add_u64 v[96:97], v[114:115], 0, v[96:97]
	v_cvt_pk_bf16_f32 v127, v90, v91
	v_lshlrev_b64 v[90:91], 10, v[124:125]
	v_mov_b64_e32 v[238:239], v[98:99]
	v_cvt_pk_bf16_f32 v126, v148, v149
	v_lshl_add_u64 v[98:99], v[116:117], 0, v[90:91]
	v_mov_b64_e32 v[242:243], v[126:127]
	v_mfma_f32_16x16x32_bf16 v[124:127], v[56:59], v[4:7], 0
	v_mfma_f32_16x16x32_bf16 v[56:59], v[60:63], v[20:23], v[52:55]
	v_mfma_f32_16x16x32_bf16 v[52:55], v[64:67], v[20:23], v[124:127]
	s_nop 5
	v_add_u32_e32 v124, v142, v138
	v_add_f32_e32 v48, v48, v56
	v_add_f32_e32 v49, v49, v57
	v_mul_f32_e32 v48, 0xbfb8aa3b, v48
	v_mul_f32_e32 v49, 0xbfb8aa3b, v49
	v_exp_f32_e32 v48, v48
	v_exp_f32_e32 v49, v49
	v_add_f32_e32 v44, v44, v52
	v_add_f32_e32 v45, v45, v53
	v_mul_f32_e32 v44, 0xbfb8aa3b, v44
	v_mul_f32_e32 v45, 0xbfb8aa3b, v45
	v_add_f32_e32 v48, 1.0, v48
	v_exp_f32_e32 v44, v44
	v_add_f32_e32 v49, 1.0, v49
	v_exp_f32_e32 v45, v45
	v_rcp_f32_e32 v56, v48
	v_rcp_f32_e32 v52, v49
	v_add_f32_e32 v44, 1.0, v44
	v_add_f32_e32 v45, 1.0, v45
	v_rcp_f32_e32 v48, v44
	v_mul_f32_e32 v44, 0xc1000000, v56
	v_rcp_f32_e32 v49, v45
	v_mul_f32_e32 v45, 0xc1000000, v52
	v_mul_f32_e32 v44, v145, v44
	v_mul_f32_e32 v45, v147, v45
	v_mul_f32_e32 v44, 0x3fb8aa3b, v44
	v_mul_f32_e32 v45, 0x3fb8aa3b, v45
	v_exp_f32_e32 v56, v44
	v_exp_f32_e32 v57, v45
	v_add_f32_e32 v50, v50, v58
	v_mul_f32_e32 v50, 0xbfb8aa3b, v50
	v_fma_f32 v44, -v56, v56, 1.0
	v_fma_f32 v45, -v57, v57, 1.0
	v_sqrt_f32_e32 v60, v44
	v_mov_b32_e32 v44, 1.0
	v_sqrt_f32_e32 v61, v45
	v_mov_b32_e32 v45, 1.0
	v_exp_f32_e32 v50, v50
	v_mov_b32_dpp v44, v56 row_shr:1 row_mask:0xf bank_mask:0xf
	v_mov_b32_dpp v45, v57 row_shr:1 row_mask:0xf bank_mask:0xf
	v_pk_mul_f32 v[62:63], v[56:57], v[44:45]
	v_mov_b32_e32 v44, 1.0
	v_mov_b32_e32 v45, 1.0
	v_add_f32_e32 v46, v46, v54
	v_mov_b32_dpp v44, v62 row_shr:2 row_mask:0xf bank_mask:0xf
	v_mov_b32_dpp v45, v63 row_shr:2 row_mask:0xf bank_mask:0xf
	v_mul_f32_e32 v46, 0xbfb8aa3b, v46
	v_pk_mul_f32 v[64:65], v[62:63], v[44:45]
	v_mov_b32_e32 v44, 1.0
	v_mov_b32_e32 v45, 1.0
	v_add_f32_e32 v50, 1.0, v50
	v_exp_f32_e32 v46, v46
	v_mov_b32_dpp v44, v64 row_shr:4 row_mask:0xf bank_mask:0xf
	v_mov_b32_dpp v45, v65 row_shr:4 row_mask:0xf bank_mask:0xf
	v_rcp_f32_e32 v50, v50
	v_pk_mul_f32 v[66:67], v[64:65], v[44:45]
	v_mov_b32_e32 v44, 1.0
	v_mov_b32_e32 v45, 1.0
	v_add_f32_e32 v46, 1.0, v46
	v_mov_b32_dpp v44, v66 row_shr:8 row_mask:0xf bank_mask:0xf
	v_mov_b32_dpp v45, v67 row_shr:8 row_mask:0xf bank_mask:0xf
	v_pk_mul_f32 v[90:91], v[66:67], v[44:45]
	v_rcp_f32_e32 v54, v46
	v_pk_mul_f32 v[52:53], v[90:91], v[122:123]
	ds_read2_b32 v[122:123], v124 offset1:1
	v_mul_f32_e32 v46, 0xc1000000, v50
	v_mul_f32_e32 v2, v2, v46
	v_mul_f32_e32 v2, 0x3fb8aa3b, v2
	v_exp_f32_e32 v50, v2
	s_waitcnt lgkmcnt(0)
; __device__ __forceinline__ unsigned pk2(float lo, float hi) { const f32x2_t v = {lo, hi}; const bf16x2_t b = __builtin_convertvector(v, bf16x2_t); return __builtin_bit_cast(unsigned, b); }
; __device__ __forceinline__ float sigmoidf_(float x) { return __builtin_amdgcn_rcpf(1.0f + __expf(-x)); }
; __device__ __forceinline__ float bcast15(float v, int lane) { return bperm_f((lane & 48) | 15, v); }
; __device__ __forceinline__ void w_lru_m1(const Args& a, int l, unsigned char* ws, const bf16_t* proj, bf16_t* y, LAS unsigned char* wl, int b, int ck_, int h, int lane) {
;     ...
;             for (int r = 0; r < 4; ++r) {
;                 const float rg = sigmoidf_(ga[r] + bav[r]), ig = sigmoidf_(gx[r] + bxv[r]);
;                 const float la = -8.0f * rg * sp[r]; float A = __expf(la);
;                 float U = __builtin_amdgcn_sqrtf(1.0f - A * A) * (ig * xcf[tok * 65 + j0 + r]);
;                 { const float As = dpp_shr1<1>(A), Us = dpp_shr0<1>(U); U = A * Us + U; A = A * As; }
;                 { const float As = dpp_shr1<2>(A), Us = dpp_shr0<2>(U); U = A * Us + U; A = A * As; }
;                 { const float As = dpp_shr1<4>(A), Us = dpp_shr0<4>(U); U = A * Us + U; A = A * As; }
;                 { const float As = dpp_shr1<8>(A), Us = dpp_shr0<8>(U); U = A * Us + U; A = A * As; }
;                 const float hh = U + A * hc[r], PP = A * Pc[r];
;                 hc[r] = bcast15(hh, lane); Pc[r] = bcast15(PP, lane); hv[r] = hh; pv[r] = PP; }
;             *(unsigned long long*)(y + (size_t)(row0 + tok) * DM + 64 * h + j0) = (unsigned long long)pk2(hv[0], hv[1]) | ((unsigned long long)pk2(hv[2], hv[3]) << 32);
;             *(unsigned long long*)((bf16_t*)(ws + WS_P) + (size_t)(row0 + tok) * 512 + 64 * h + j0) = (unsigned long long)pk2(pv[0], pv[1]) | ((unsigned long long)pk2(pv[2], pv[3]) << 32);
;         }
;         if (lo == 0) { const size_t so = (size_t)(b * NCH + ck_) * 512 + 64 * h + j0;
; #pragma unroll
;             for (int r = 0; r < 4; ++r) { ((float*)(ws + WS_LRUA))[so + r] = Pc[r]; ((float*)(ws + WS_LRUH))[so + r] = hc[r]; } }
	v_pk_mul_f32 v[48:49], v[122:123], v[48:49]
	v_add_f32_e32 v47, v47, v55
	v_pk_mul_f32 v[48:49], v[48:49], v[60:61]
	v_fma_f32 v2, -v50, v50, 1.0
	v_mul_f32_e32 v47, 0xbfb8aa3b, v47
	v_mov_b32_dpp v60, v48 row_shr:1 row_mask:0xf bank_mask:0xf bound_ctrl:1
	v_mov_b32_dpp v61, v49 row_shr:1 row_mask:0xf bank_mask:0xf bound_ctrl:1
	v_pk_fma_f32 v[48:49], v[56:57], v[60:61], v[48:49]
	v_sqrt_f32_e32 v60, v2
	v_add_f32_e32 v2, v51, v59
	v_mul_f32_e32 v2, 0xbfb8aa3b, v2
	v_exp_f32_e32 v2, v2
	v_exp_f32_e32 v47, v47
	v_mov_b32_e32 v46, 1.0
	v_mov_b32_dpp v56, v48 row_shr:2 row_mask:0xf bank_mask:0xf bound_ctrl:1
	v_add_f32_e32 v2, 1.0, v2
	v_rcp_f32_e32 v2, v2
	v_add_f32_e32 v47, 1.0, v47
	v_rcp_f32_e32 v55, v47
	v_mov_b32_e32 v47, 1.0
	v_mul_f32_e32 v2, 0xc1000000, v2
	v_mul_f32_e32 v2, v146, v2
	v_mul_f32_e32 v2, 0x3fb8aa3b, v2
	v_exp_f32_e32 v51, v2
	v_mov_b32_dpp v57, v49 row_shr:2 row_mask:0xf bank_mask:0xf bound_ctrl:1
	v_mov_b32_dpp v46, v50 row_shr:1 row_mask:0xf bank_mask:0xf
	v_pk_fma_f32 v[48:49], v[62:63], v[56:57], v[48:49]
	v_mov_b32_dpp v47, v51 row_shr:1 row_mask:0xf bank_mask:0xf
	v_pk_mul_f32 v[62:63], v[50:51], v[46:47]
	v_mov_b32_e32 v46, 1.0
	v_mov_b32_e32 v47, 1.0
	v_mov_b32_dpp v56, v48 row_shr:4 row_mask:0xf bank_mask:0xf bound_ctrl:1
	v_mov_b32_dpp v57, v49 row_shr:4 row_mask:0xf bank_mask:0xf bound_ctrl:1
	v_mov_b32_dpp v46, v62 row_shr:2 row_mask:0xf bank_mask:0xf
	v_mov_b32_dpp v47, v63 row_shr:2 row_mask:0xf bank_mask:0xf
	v_pk_fma_f32 v[48:49], v[64:65], v[56:57], v[48:49]
	v_pk_mul_f32 v[64:65], v[62:63], v[46:47]
	v_mov_b32_e32 v46, 1.0
	v_mov_b32_e32 v47, 1.0
	v_mov_b32_dpp v56, v48 row_shr:8 row_mask:0xf bank_mask:0xf bound_ctrl:1
	v_mov_b32_dpp v57, v49 row_shr:8 row_mask:0xf bank_mask:0xf bound_ctrl:1
	v_mov_b32_dpp v46, v64 row_shr:4 row_mask:0xf bank_mask:0xf
	v_mov_b32_dpp v47, v65 row_shr:4 row_mask:0xf bank_mask:0xf
	v_pk_fma_f32 v[48:49], v[66:67], v[56:57], v[48:49]
	v_pk_mul_f32 v[66:67], v[64:65], v[46:47]
	v_mov_b32_e32 v46, 1.0
	v_mov_b32_e32 v47, 1.0
	v_pk_fma_f32 v[56:57], v[90:91], v[94:95], v[48:49]
	v_mov_b32_dpp v46, v66 row_shr:8 row_mask:0xf bank_mask:0xf
	v_mov_b32_dpp v47, v67 row_shr:8 row_mask:0xf bank_mask:0xf
	v_pk_mul_f32 v[90:91], v[66:67], v[46:47]
	v_fma_f32 v2, -v51, v51, 1.0
	v_pk_mul_f32 v[58:59], v[90:91], v[92:93]
	ds_read2_b32 v[92:93], v124 offset0:2 offset1:3
	v_sqrt_f32_e32 v61, v2
	ds_bpermute_b32 v44, v143, v52 offset:60
	ds_bpermute_b32 v48, v143, v56 offset:60
	ds_bpermute_b32 v49, v143, v57 offset:60
	s_waitcnt lgkmcnt(0)
	v_pk_mul_f32 v[54:55], v[54:55], v[92:93]
	ds_bpermute_b32 v45, v143, v53 offset:60
	v_pk_mul_f32 v[54:55], v[60:61], v[54:55]
	ds_bpermute_b32 v46, v143, v58 offset:60
	ds_bpermute_b32 v47, v143, v59 offset:60
	v_mov_b32_dpp v60, v54 row_shr:1 row_mask:0xf bank_mask:0xf bound_ctrl:1
	v_mov_b32_dpp v61, v55 row_shr:1 row_mask:0xf bank_mask:0xf bound_ctrl:1
	v_pk_fma_f32 v[50:51], v[50:51], v[60:61], v[54:55]
	v_cvt_pk_bf16_f32 v56, v56, v57
	v_cvt_pk_bf16_f32 v52, v52, v53
	v_mov_b32_dpp v54, v50 row_shr:2 row_mask:0xf bank_mask:0xf bound_ctrl:1
	v_mov_b32_dpp v55, v51 row_shr:2 row_mask:0xf bank_mask:0xf bound_ctrl:1
	v_pk_fma_f32 v[50:51], v[62:63], v[54:55], v[50:51]
	v_cvt_pk_bf16_f32 v53, v58, v59
	s_nop 0
	v_mov_b32_dpp v54, v50 row_shr:4 row_mask:0xf bank_mask:0xf bound_ctrl:1
	v_mov_b32_dpp v55, v51 row_shr:4 row_mask:0xf bank_mask:0xf bound_ctrl:1
	v_pk_fma_f32 v[50:51], v[64:65], v[54:55], v[50:51]
	s_nop 1
	v_mov_b32_dpp v54, v50 row_shr:8 row_mask:0xf bank_mask:0xf bound_ctrl:1
	v_mov_b32_dpp v55, v51 row_shr:8 row_mask:0xf bank_mask:0xf bound_ctrl:1
	v_pk_fma_f32 v[50:51], v[66:67], v[54:55], v[50:51]
	s_nop 0
	v_pk_fma_f32 v[54:55], v[90:91], v[88:89], v[50:51]
	ds_bpermute_b32 v50, v143, v54 offset:60
	ds_bpermute_b32 v51, v143, v55 offset:60
	v_cvt_pk_bf16_f32 v57, v54, v55
	v_or_b32_e32 v54, s48, v137
	v_ashrrev_i32_e32 v55, 31, v54
	v_lshlrev_b64 v[60:61], 11, v[54:55]
	v_lshlrev_b64 v[54:55], 10, v[54:55]
	v_lshl_add_u64 v[114:115], v[114:115], 0, v[60:61]
	v_lshl_add_u64 v[116:117], v[116:117], 0, v[54:55]
	v_mov_b64_e32 v[246:247], v[56:57]
	v_mov_b64_e32 v[250:251], v[52:53]
	s_and_saveexec_b64 s[34:35], vcc
	s_cbranch_execz .LBB0_523
	v_lshl_add_u64 v[52:53], s[42:43], 0, v[0:1]
	v_lshlrev_b64 v[52:53], 2, v[52:53]
	v_lshl_add_u64 v[54:55], s[84:85], 0, v[52:53]
	v_lshl_add_u64 v[52:53], s[86:87], 0, v[52:53]
	s_waitcnt lgkmcnt(0)
	global_store_dwordx4 v[54:55], v[44:47], off
	global_store_dwordx4 v[52:53], v[48:51], off
